# GEMM epilogues Epi5/EpiKV/EpiQ: the eight row statistics loaded up front instead of one serialised round trip (with a store drain) per row
# speedup vs baseline: 1.0058x; 1.0058x over previous
.LBB0_564:
	v_lshl_add_u32 v146, s8, 8, v150
	v_ashrrev_i32_e32 v147, 31, v146
	v_lshl_add_u64 v[148:149], v[146:147], 2, s[38:39]
	global_load_dword v158, v[148:149], off
	global_load_dword v237, v[148:149], off offset:64
	global_load_dword v238, v[148:149], off offset:128
	global_load_dword v239, v[148:149], off offset:192
	global_load_dword v240, v[148:149], off offset:512
	global_load_dword v241, v[148:149], off offset:576
	global_load_dword v242, v[148:149], off offset:640
	global_load_dword v243, v[148:149], off offset:704
	s_cmp_lg_u32 s0, 2
	v_mov_b64_e32 v[156:157], s[84:85]
	s_cselect_b64 s[12:13], -1, 0
	s_lshl_b32 s56, s0, 8
	v_mad_i64_i32 v[156:157], s[8:9], v146, s94, v[156:157]
	s_ashr_i32 s57, s56, 31
	v_lshl_add_u64 v[156:157], s[56:57], 1, v[156:157]
	v_lshl_add_u64 v[160:161], v[156:157], 0, v[136:137]
	s_cmp_eq_u32 s0, 2
	s_waitcnt vmcnt(0)
	v_fmamk_f32 v158, v158, 0x3a000000, v155
	v_mul_f32_e32 v159, 0x4b800000, v158
	v_cmp_gt_f32_e32 vcc, s93, v158
	s_nop 1
	v_cndmask_b32_e32 v158, v158, v159, vcc
	v_rsq_f32_e32 v158, v158
	s_nop 0
	v_mul_f32_e32 v156, 0x45800000, v158
	v_cndmask_b32_e32 v156, v158, v156, vcc
	v_pk_mul_f32 v[126:127], v[126:127], v[156:157] op_sel_hi:[1,0]
	v_pk_mul_f32 v[158:159], v[124:125], v[156:157] op_sel_hi:[1,0]
	v_pk_mul_f32 v[162:163], v[122:123], v[156:157] op_sel_hi:[1,0]
	v_pk_mul_f32 v[164:165], v[120:121], v[156:157] op_sel_hi:[1,0]
	v_pk_mul_f32 v[120:121], v[112:113], v[156:157] op_sel_hi:[1,0]
	v_cvt_pk_bf16_f32 v122, v158, v159
	v_cvt_pk_bf16_f32 v123, v126, v127
	v_cvt_pk_bf16_f32 v124, v164, v165
	v_cvt_pk_bf16_f32 v125, v162, v163
	v_mov_b32_e32 v113, v164
	v_mov_b32_e32 v164, v159
	v_mov_b32_e32 v167, v162
	v_mov_b32_e32 v162, v127
	v_mov_b32_e32 v112, v158
	v_mov_b32_e32 v166, v126
	global_store_dwordx4 v[160:161], v[122:125], off
	v_pk_mul_f32 v[118:119], v[118:119], v[156:157] op_sel_hi:[1,0]
	v_pk_mul_f32 v[116:117], v[116:117], v[156:157] op_sel_hi:[1,0]
	v_pk_mul_f32 v[122:123], v[164:165], v[164:165]
	v_pk_mul_f32 v[124:125], v[162:163], v[162:163]
	v_pk_fma_f32 v[112:113], v[112:113], v[112:113], v[122:123]
	v_pk_fma_f32 v[122:123], v[166:167], v[166:167], v[124:125]
	v_pk_mul_f32 v[114:115], v[114:115], v[156:157] op_sel_hi:[1,0]
	v_pk_add_f32 v[112:113], v[112:113], v[122:123]
	v_cvt_pk_bf16_f32 v156, v116, v117
	v_cvt_pk_bf16_f32 v157, v118, v119
	v_cvt_pk_bf16_f32 v158, v120, v121
	v_cvt_pk_bf16_f32 v159, v114, v115
	v_pk_add_f32 v[112:113], v[112:113], v[112:113] op_sel:[0,1] op_sel_hi:[1,0]
	global_store_dwordx4 v[160:161], v[156:159], off offset:256
	s_cbranch_scc1 .LBB0_566
	v_mov_b32_e32 v123, v120
	v_mov_b32_e32 v120, v117
	v_mov_b32_e32 v122, v116
	v_pk_mul_f32 v[116:117], v[120:121], v[120:121]
	v_mov_b32_e32 v121, v114
	v_mov_b32_e32 v114, v119
	v_mov_b32_e32 v120, v118
	v_pk_mul_f32 v[114:115], v[114:115], v[114:115]
	v_pk_fma_f32 v[116:117], v[122:123], v[122:123], v[116:117]
	v_pk_fma_f32 v[114:115], v[120:121], v[120:121], v[114:115]
	s_nop 0
	v_pk_add_f32 v[114:115], v[116:117], v[114:115]
	s_nop 0
	v_add_f32_e32 v113, v114, v115
	v_add_f32_e32 v112, v112, v113

.LBB0_570:
	v_or_b32_e32 v112, 16, v146
	s_waitcnt lgkmcnt(0)
	v_ashrrev_i32_e32 v113, 31, v112
	v_lshl_add_u64 v[114:115], v[112:113], 2, s[38:39]
	v_mov_b32_e32 v116, v237
	v_mov_b64_e32 v[114:115], s[84:85]
	v_mad_i64_i32 v[112:113], s[0:1], v112, s94, v[114:115]
	v_lshl_add_u64 v[112:113], s[56:57], 1, v[112:113]
	v_cndmask_b32_e64 v117, 0, 1, s[12:13]
	v_cmp_ne_u32_e64 s[0:1], 1, v117
	s_andn2_b64 vcc, exec, s[12:13]
	v_fmamk_f32 v114, v116, 0x3a000000, v155
	v_mul_f32_e32 v115, 0x4b800000, v114
	v_cmp_gt_f32_e64 s[8:9], s93, v114
	s_nop 1
	v_cndmask_b32_e64 v114, v114, v115, s[8:9]
	v_rsq_f32_e32 v116, v114
	v_lshl_add_u64 v[114:115], v[112:113], 0, v[136:137]
	v_mul_f32_e32 v112, 0x45800000, v116
	v_cndmask_b32_e64 v112, v116, v112, s[8:9]
	v_pk_mul_f32 v[110:111], v[110:111], v[112:113] op_sel_hi:[1,0]
	v_pk_mul_f32 v[116:117], v[108:109], v[112:113] op_sel_hi:[1,0]
	v_pk_mul_f32 v[118:119], v[106:107], v[112:113] op_sel_hi:[1,0]
	v_pk_mul_f32 v[120:121], v[104:105], v[112:113] op_sel_hi:[1,0]
	v_pk_mul_f32 v[104:105], v[96:97], v[112:113] op_sel_hi:[1,0]
	v_cvt_pk_bf16_f32 v106, v116, v117
	v_cvt_pk_bf16_f32 v107, v110, v111
	v_cvt_pk_bf16_f32 v108, v120, v121
	v_cvt_pk_bf16_f32 v109, v118, v119
	v_mov_b32_e32 v97, v120
	v_mov_b32_e32 v120, v117
	v_mov_b32_e32 v117, v118
	v_mov_b32_e32 v118, v111
	v_mov_b32_e32 v96, v116
	v_mov_b32_e32 v116, v110
	global_store_dwordx4 v[114:115], v[106:109], off
	v_pk_mul_f32 v[102:103], v[102:103], v[112:113] op_sel_hi:[1,0]
	v_pk_mul_f32 v[100:101], v[100:101], v[112:113] op_sel_hi:[1,0]
	v_pk_mul_f32 v[106:107], v[120:121], v[120:121]
	v_pk_mul_f32 v[108:109], v[118:119], v[118:119]
	v_pk_fma_f32 v[96:97], v[96:97], v[96:97], v[106:107]
	v_pk_fma_f32 v[106:107], v[116:117], v[116:117], v[108:109]
	v_pk_mul_f32 v[98:99], v[98:99], v[112:113] op_sel_hi:[1,0]
	v_pk_add_f32 v[96:97], v[96:97], v[106:107]
	v_cvt_pk_bf16_f32 v110, v100, v101
	v_cvt_pk_bf16_f32 v111, v102, v103
	v_cvt_pk_bf16_f32 v112, v104, v105
	v_cvt_pk_bf16_f32 v113, v98, v99
	v_pk_add_f32 v[96:97], v[96:97], v[96:97] op_sel:[0,1] op_sel_hi:[1,0]
	global_store_dwordx4 v[114:115], v[110:113], off offset:256
	s_cbranch_vccnz .LBB0_572
	v_mov_b32_e32 v107, v104
	v_mov_b32_e32 v104, v101
	v_mov_b32_e32 v106, v100
	v_pk_mul_f32 v[100:101], v[104:105], v[104:105]
	v_mov_b32_e32 v105, v98
	v_mov_b32_e32 v98, v103
	v_mov_b32_e32 v104, v102
	v_pk_mul_f32 v[98:99], v[98:99], v[98:99]
	v_pk_fma_f32 v[100:101], v[106:107], v[106:107], v[100:101]
	v_pk_fma_f32 v[98:99], v[104:105], v[104:105], v[98:99]
	s_nop 0
	v_pk_add_f32 v[98:99], v[100:101], v[98:99]
	s_nop 0
	v_add_f32_e32 v97, v98, v99
	v_add_f32_e32 v96, v96, v97

.LBB0_576:
	v_or_b32_e32 v96, 32, v146
	s_waitcnt lgkmcnt(0)
	v_ashrrev_i32_e32 v97, 31, v96
	v_lshl_add_u64 v[98:99], v[96:97], 2, s[38:39]
	v_mov_b32_e32 v97, v238
	v_mov_b64_e32 v[98:99], s[84:85]
	s_and_b64 vcc, exec, s[0:1]
	v_fmamk_f32 v97, v97, 0x3a000000, v155
	v_mul_f32_e32 v100, 0x4b800000, v97
	v_cmp_gt_f32_e64 s[12:13], s93, v97
	s_nop 1
	v_cndmask_b32_e64 v97, v97, v100, s[12:13]
	v_rsq_f32_e32 v100, v97
	v_mad_i64_i32 v[96:97], s[64:65], v96, s94, v[98:99]
	v_lshl_add_u64 v[96:97], s[56:57], 1, v[96:97]
	v_lshl_add_u64 v[98:99], v[96:97], 0, v[136:137]
	v_mul_f32_e32 v96, 0x45800000, v100
	v_cndmask_b32_e64 v96, v100, v96, s[12:13]
	v_pk_mul_f32 v[94:95], v[94:95], v[96:97] op_sel_hi:[1,0]
	v_pk_mul_f32 v[100:101], v[92:93], v[96:97] op_sel_hi:[1,0]
	v_pk_mul_f32 v[102:103], v[90:91], v[96:97] op_sel_hi:[1,0]
	v_pk_mul_f32 v[104:105], v[88:89], v[96:97] op_sel_hi:[1,0]
	v_pk_mul_f32 v[88:89], v[80:81], v[96:97] op_sel_hi:[1,0]
	v_cvt_pk_bf16_f32 v90, v100, v101
	v_cvt_pk_bf16_f32 v91, v94, v95
	v_cvt_pk_bf16_f32 v92, v104, v105
	v_cvt_pk_bf16_f32 v93, v102, v103
	v_mov_b32_e32 v81, v104
	v_mov_b32_e32 v104, v101
	v_mov_b32_e32 v101, v102
	v_mov_b32_e32 v102, v95
	v_mov_b32_e32 v80, v100
	v_mov_b32_e32 v100, v94
	global_store_dwordx4 v[98:99], v[90:93], off
	v_pk_mul_f32 v[86:87], v[86:87], v[96:97] op_sel_hi:[1,0]
	v_pk_mul_f32 v[84:85], v[84:85], v[96:97] op_sel_hi:[1,0]
	v_pk_mul_f32 v[90:91], v[104:105], v[104:105]
	v_pk_mul_f32 v[92:93], v[102:103], v[102:103]
	v_pk_fma_f32 v[80:81], v[80:81], v[80:81], v[90:91]
	v_pk_fma_f32 v[90:91], v[100:101], v[100:101], v[92:93]
	v_pk_mul_f32 v[82:83], v[82:83], v[96:97] op_sel_hi:[1,0]
	v_pk_add_f32 v[80:81], v[80:81], v[90:91]
	v_cvt_pk_bf16_f32 v94, v84, v85
	v_cvt_pk_bf16_f32 v95, v86, v87
	v_cvt_pk_bf16_f32 v96, v88, v89
	v_cvt_pk_bf16_f32 v97, v82, v83
	v_pk_add_f32 v[80:81], v[80:81], v[80:81] op_sel:[0,1] op_sel_hi:[1,0]
	global_store_dwordx4 v[98:99], v[94:97], off offset:256
	s_cbranch_vccnz .LBB0_578
	v_mov_b32_e32 v91, v88
	v_mov_b32_e32 v88, v85
	v_mov_b32_e32 v90, v84
	v_pk_mul_f32 v[84:85], v[88:89], v[88:89]
	v_mov_b32_e32 v89, v82
	v_mov_b32_e32 v82, v87
	v_mov_b32_e32 v88, v86
	v_pk_mul_f32 v[82:83], v[82:83], v[82:83]
	v_pk_fma_f32 v[84:85], v[90:91], v[90:91], v[84:85]
	v_pk_fma_f32 v[82:83], v[88:89], v[88:89], v[82:83]
	s_nop 0
	v_pk_add_f32 v[82:83], v[84:85], v[82:83]
	s_nop 0
	v_add_f32_e32 v81, v82, v83
	v_add_f32_e32 v80, v80, v81

.LBB0_582:
	v_or_b32_e32 v80, 48, v146
	s_waitcnt lgkmcnt(0)
	v_ashrrev_i32_e32 v81, 31, v80
	v_lshl_add_u64 v[82:83], v[80:81], 2, s[38:39]
	v_mov_b32_e32 v81, v239
	v_mov_b64_e32 v[82:83], s[84:85]
	s_and_b64 vcc, exec, s[0:1]
	v_fmamk_f32 v81, v81, 0x3a000000, v155
	v_mul_f32_e32 v84, 0x4b800000, v81
	v_cmp_gt_f32_e64 s[12:13], s93, v81
	s_nop 1
	v_cndmask_b32_e64 v81, v81, v84, s[12:13]
	v_rsq_f32_e32 v84, v81
	v_mad_i64_i32 v[80:81], s[64:65], v80, s94, v[82:83]
	v_lshl_add_u64 v[80:81], s[56:57], 1, v[80:81]
	v_lshl_add_u64 v[82:83], v[80:81], 0, v[136:137]
	v_mul_f32_e32 v80, 0x45800000, v84
	v_cndmask_b32_e64 v80, v84, v80, s[12:13]
	v_pk_mul_f32 v[78:79], v[78:79], v[80:81] op_sel_hi:[1,0]
	v_pk_mul_f32 v[84:85], v[76:77], v[80:81] op_sel_hi:[1,0]
	v_pk_mul_f32 v[86:87], v[74:75], v[80:81] op_sel_hi:[1,0]
	v_pk_mul_f32 v[88:89], v[72:73], v[80:81] op_sel_hi:[1,0]
	v_pk_mul_f32 v[72:73], v[64:65], v[80:81] op_sel_hi:[1,0]
	v_cvt_pk_bf16_f32 v74, v84, v85
	v_cvt_pk_bf16_f32 v75, v78, v79
	v_cvt_pk_bf16_f32 v76, v88, v89
	v_cvt_pk_bf16_f32 v77, v86, v87
	v_mov_b32_e32 v65, v88
	v_mov_b32_e32 v88, v85
	v_mov_b32_e32 v85, v86
	v_mov_b32_e32 v86, v79
	v_mov_b32_e32 v64, v84
	v_mov_b32_e32 v84, v78
	global_store_dwordx4 v[82:83], v[74:77], off
	v_pk_mul_f32 v[70:71], v[70:71], v[80:81] op_sel_hi:[1,0]
	v_pk_mul_f32 v[68:69], v[68:69], v[80:81] op_sel_hi:[1,0]
	v_pk_mul_f32 v[74:75], v[88:89], v[88:89]
	v_pk_mul_f32 v[76:77], v[86:87], v[86:87]
	v_pk_fma_f32 v[64:65], v[64:65], v[64:65], v[74:75]
	v_pk_fma_f32 v[74:75], v[84:85], v[84:85], v[76:77]
	v_pk_mul_f32 v[66:67], v[66:67], v[80:81] op_sel_hi:[1,0]
	v_pk_add_f32 v[64:65], v[64:65], v[74:75]
	v_cvt_pk_bf16_f32 v78, v68, v69
	v_cvt_pk_bf16_f32 v79, v70, v71
	v_cvt_pk_bf16_f32 v80, v72, v73
	v_cvt_pk_bf16_f32 v81, v66, v67
	v_pk_add_f32 v[64:65], v[64:65], v[64:65] op_sel:[0,1] op_sel_hi:[1,0]
	global_store_dwordx4 v[82:83], v[78:81], off offset:256
	s_cbranch_vccnz .LBB0_584
	v_mov_b32_e32 v75, v72
	v_mov_b32_e32 v72, v69
	v_mov_b32_e32 v74, v68
	v_pk_mul_f32 v[68:69], v[72:73], v[72:73]
	v_mov_b32_e32 v73, v66
	v_mov_b32_e32 v66, v71
	v_mov_b32_e32 v72, v70
	v_pk_mul_f32 v[66:67], v[66:67], v[66:67]
	v_pk_fma_f32 v[68:69], v[74:75], v[74:75], v[68:69]
	v_pk_fma_f32 v[66:67], v[72:73], v[72:73], v[66:67]
	s_nop 0
	v_pk_add_f32 v[66:67], v[68:69], v[66:67]
	s_nop 0
	v_add_f32_e32 v65, v66, v67
	v_add_f32_e32 v64, v64, v65

.LBB0_588:
	v_mov_b32_e32 v66, v240
	v_add_u32_e32 v67, 0x80, v146
	s_waitcnt lgkmcnt(0)
	v_mov_b64_e32 v[64:65], s[84:85]
	v_mad_i64_i32 v[64:65], s[64:65], v67, s94, v[64:65]
	v_lshl_add_u64 v[64:65], s[56:57], 1, v[64:65]
	s_and_b64 vcc, exec, s[0:1]
	v_fmamk_f32 v66, v66, 0x3a000000, v155
	v_mul_f32_e32 v68, 0x4b800000, v66
	v_cmp_gt_f32_e64 s[12:13], s93, v66
	s_nop 1
	v_cndmask_b32_e64 v66, v66, v68, s[12:13]
	v_rsq_f32_e32 v68, v66
	v_lshl_add_u64 v[66:67], v[64:65], 0, v[136:137]
	v_mul_f32_e32 v64, 0x45800000, v68
	v_cndmask_b32_e64 v64, v68, v64, s[12:13]
	v_pk_mul_f32 v[62:63], v[62:63], v[64:65] op_sel_hi:[1,0]
	v_pk_mul_f32 v[68:69], v[60:61], v[64:65] op_sel_hi:[1,0]
	v_pk_mul_f32 v[70:71], v[58:59], v[64:65] op_sel_hi:[1,0]
	v_pk_mul_f32 v[72:73], v[56:57], v[64:65] op_sel_hi:[1,0]
	v_pk_mul_f32 v[56:57], v[48:49], v[64:65] op_sel_hi:[1,0]
	v_cvt_pk_bf16_f32 v58, v68, v69
	v_cvt_pk_bf16_f32 v59, v62, v63
	v_cvt_pk_bf16_f32 v60, v72, v73
	v_cvt_pk_bf16_f32 v61, v70, v71
	v_mov_b32_e32 v49, v72
	v_mov_b32_e32 v72, v69
	v_mov_b32_e32 v69, v70
	v_mov_b32_e32 v70, v63
	v_mov_b32_e32 v48, v68
	v_mov_b32_e32 v68, v62
	global_store_dwordx4 v[66:67], v[58:61], off
	v_pk_mul_f32 v[54:55], v[54:55], v[64:65] op_sel_hi:[1,0]
	v_pk_mul_f32 v[52:53], v[52:53], v[64:65] op_sel_hi:[1,0]
	v_pk_mul_f32 v[58:59], v[72:73], v[72:73]
	v_pk_mul_f32 v[60:61], v[70:71], v[70:71]
	v_pk_fma_f32 v[48:49], v[48:49], v[48:49], v[58:59]
	v_pk_fma_f32 v[58:59], v[68:69], v[68:69], v[60:61]
	v_pk_mul_f32 v[50:51], v[50:51], v[64:65] op_sel_hi:[1,0]
	v_pk_add_f32 v[48:49], v[48:49], v[58:59]
	v_cvt_pk_bf16_f32 v62, v52, v53
	v_cvt_pk_bf16_f32 v63, v54, v55
	v_cvt_pk_bf16_f32 v64, v56, v57
	v_cvt_pk_bf16_f32 v65, v50, v51
	v_pk_add_f32 v[48:49], v[48:49], v[48:49] op_sel:[0,1] op_sel_hi:[1,0]
	global_store_dwordx4 v[66:67], v[62:65], off offset:256
	s_cbranch_vccnz .LBB0_590
	v_mov_b32_e32 v59, v56
	v_mov_b32_e32 v56, v53
	v_mov_b32_e32 v58, v52
	v_pk_mul_f32 v[52:53], v[56:57], v[56:57]
	v_mov_b32_e32 v57, v50
	v_mov_b32_e32 v50, v55
	v_mov_b32_e32 v56, v54
	v_pk_mul_f32 v[50:51], v[50:51], v[50:51]
	v_pk_fma_f32 v[52:53], v[58:59], v[58:59], v[52:53]
	v_pk_fma_f32 v[50:51], v[56:57], v[56:57], v[50:51]
	s_nop 0
	v_pk_add_f32 v[50:51], v[52:53], v[50:51]
	s_nop 0
	v_add_f32_e32 v49, v50, v51
	v_add_f32_e32 v48, v48, v49

.LBB0_594:
	v_mov_b32_e32 v50, v241
	v_add_u32_e32 v51, 0x90, v146
	s_waitcnt lgkmcnt(0)
	v_mov_b64_e32 v[48:49], s[84:85]
	v_mad_i64_i32 v[48:49], s[64:65], v51, s94, v[48:49]
	v_lshl_add_u64 v[48:49], s[56:57], 1, v[48:49]
	s_and_b64 vcc, exec, s[0:1]
	v_fmamk_f32 v50, v50, 0x3a000000, v155
	v_mul_f32_e32 v52, 0x4b800000, v50
	v_cmp_gt_f32_e64 s[12:13], s93, v50
	s_nop 1
	v_cndmask_b32_e64 v50, v50, v52, s[12:13]
	v_rsq_f32_e32 v52, v50
	v_lshl_add_u64 v[50:51], v[48:49], 0, v[136:137]
	v_mul_f32_e32 v48, 0x45800000, v52
	v_cndmask_b32_e64 v48, v52, v48, s[12:13]
	v_pk_mul_f32 v[46:47], v[46:47], v[48:49] op_sel_hi:[1,0]
	v_pk_mul_f32 v[52:53], v[44:45], v[48:49] op_sel_hi:[1,0]
	v_pk_mul_f32 v[54:55], v[42:43], v[48:49] op_sel_hi:[1,0]
	v_pk_mul_f32 v[56:57], v[40:41], v[48:49] op_sel_hi:[1,0]
	v_pk_mul_f32 v[40:41], v[32:33], v[48:49] op_sel_hi:[1,0]
	v_cvt_pk_bf16_f32 v42, v52, v53
	v_cvt_pk_bf16_f32 v43, v46, v47
	v_cvt_pk_bf16_f32 v44, v56, v57
	v_cvt_pk_bf16_f32 v45, v54, v55
	v_mov_b32_e32 v33, v56
	v_mov_b32_e32 v56, v53
	v_mov_b32_e32 v53, v54
	v_mov_b32_e32 v54, v47
	v_mov_b32_e32 v32, v52
	v_mov_b32_e32 v52, v46
	global_store_dwordx4 v[50:51], v[42:45], off
	v_pk_mul_f32 v[38:39], v[38:39], v[48:49] op_sel_hi:[1,0]
	v_pk_mul_f32 v[36:37], v[36:37], v[48:49] op_sel_hi:[1,0]
	v_pk_mul_f32 v[42:43], v[56:57], v[56:57]
	v_pk_mul_f32 v[44:45], v[54:55], v[54:55]
	v_pk_fma_f32 v[32:33], v[32:33], v[32:33], v[42:43]
	v_pk_fma_f32 v[42:43], v[52:53], v[52:53], v[44:45]
	v_pk_mul_f32 v[34:35], v[34:35], v[48:49] op_sel_hi:[1,0]
	v_pk_add_f32 v[32:33], v[32:33], v[42:43]
	v_cvt_pk_bf16_f32 v46, v36, v37
	v_cvt_pk_bf16_f32 v47, v38, v39
	v_cvt_pk_bf16_f32 v48, v40, v41
	v_cvt_pk_bf16_f32 v49, v34, v35
	v_pk_add_f32 v[32:33], v[32:33], v[32:33] op_sel:[0,1] op_sel_hi:[1,0]
	global_store_dwordx4 v[50:51], v[46:49], off offset:256
	s_cbranch_vccnz .LBB0_596
	v_mov_b32_e32 v43, v40
	v_mov_b32_e32 v40, v37
	v_mov_b32_e32 v42, v36
	v_pk_mul_f32 v[36:37], v[40:41], v[40:41]
	v_mov_b32_e32 v41, v34
	v_mov_b32_e32 v34, v39
	v_mov_b32_e32 v40, v38
	v_pk_mul_f32 v[34:35], v[34:35], v[34:35]
	v_pk_fma_f32 v[36:37], v[42:43], v[42:43], v[36:37]
	v_pk_fma_f32 v[34:35], v[40:41], v[40:41], v[34:35]
	s_nop 0
	v_pk_add_f32 v[34:35], v[36:37], v[34:35]
	s_nop 0
	v_add_f32_e32 v33, v34, v35
	v_add_f32_e32 v32, v32, v33

.LBB0_600:
	v_mov_b32_e32 v34, v242
	v_add_u32_e32 v35, 0xa0, v146
	s_waitcnt lgkmcnt(0)
	v_mov_b64_e32 v[32:33], s[84:85]
	v_mad_i64_i32 v[32:33], s[64:65], v35, s94, v[32:33]
	v_lshl_add_u64 v[32:33], s[56:57], 1, v[32:33]
	s_and_b64 vcc, exec, s[0:1]
	v_fmamk_f32 v34, v34, 0x3a000000, v155
	v_mul_f32_e32 v36, 0x4b800000, v34
	v_cmp_gt_f32_e64 s[12:13], s93, v34
	s_nop 1
	v_cndmask_b32_e64 v34, v34, v36, s[12:13]
	v_rsq_f32_e32 v36, v34
	v_lshl_add_u64 v[34:35], v[32:33], 0, v[136:137]
	v_mul_f32_e32 v32, 0x45800000, v36
	v_cndmask_b32_e64 v32, v36, v32, s[12:13]
	v_pk_mul_f32 v[30:31], v[30:31], v[32:33] op_sel_hi:[1,0]
	v_pk_mul_f32 v[36:37], v[28:29], v[32:33] op_sel_hi:[1,0]
	v_pk_mul_f32 v[38:39], v[26:27], v[32:33] op_sel_hi:[1,0]
	v_pk_mul_f32 v[40:41], v[24:25], v[32:33] op_sel_hi:[1,0]
	v_pk_mul_f32 v[24:25], v[16:17], v[32:33] op_sel_hi:[1,0]
	v_cvt_pk_bf16_f32 v26, v36, v37
	v_cvt_pk_bf16_f32 v27, v30, v31
	v_cvt_pk_bf16_f32 v28, v40, v41
	v_cvt_pk_bf16_f32 v29, v38, v39
	v_mov_b32_e32 v17, v40
	v_mov_b32_e32 v40, v37
	v_mov_b32_e32 v37, v38
	v_mov_b32_e32 v38, v31
	v_mov_b32_e32 v16, v36
	v_mov_b32_e32 v36, v30
	global_store_dwordx4 v[34:35], v[26:29], off
	v_pk_mul_f32 v[22:23], v[22:23], v[32:33] op_sel_hi:[1,0]
	v_pk_mul_f32 v[20:21], v[20:21], v[32:33] op_sel_hi:[1,0]
	v_pk_mul_f32 v[26:27], v[40:41], v[40:41]
	v_pk_mul_f32 v[28:29], v[38:39], v[38:39]
	v_pk_fma_f32 v[16:17], v[16:17], v[16:17], v[26:27]
	v_pk_fma_f32 v[26:27], v[36:37], v[36:37], v[28:29]
	v_pk_mul_f32 v[18:19], v[18:19], v[32:33] op_sel_hi:[1,0]
	v_pk_add_f32 v[16:17], v[16:17], v[26:27]
	v_cvt_pk_bf16_f32 v30, v20, v21
	v_cvt_pk_bf16_f32 v31, v22, v23
	v_cvt_pk_bf16_f32 v32, v24, v25
	v_cvt_pk_bf16_f32 v33, v18, v19
	v_pk_add_f32 v[16:17], v[16:17], v[16:17] op_sel:[0,1] op_sel_hi:[1,0]
	global_store_dwordx4 v[34:35], v[30:33], off offset:256
	s_cbranch_vccnz .LBB0_602
	v_mov_b32_e32 v27, v24
	v_mov_b32_e32 v24, v21
	v_mov_b32_e32 v26, v20
	v_pk_mul_f32 v[20:21], v[24:25], v[24:25]
	v_mov_b32_e32 v25, v18
	v_mov_b32_e32 v18, v23
	v_mov_b32_e32 v24, v22
	v_pk_mul_f32 v[18:19], v[18:19], v[18:19]
	v_pk_fma_f32 v[20:21], v[26:27], v[26:27], v[20:21]
	v_pk_fma_f32 v[18:19], v[24:25], v[24:25], v[18:19]
	s_nop 0
	v_pk_add_f32 v[18:19], v[20:21], v[18:19]
	s_nop 0
	v_add_f32_e32 v17, v18, v19
	v_add_f32_e32 v16, v16, v17

.LBB0_606:
	v_mov_b32_e32 v18, v243
	s_and_b64 vcc, exec, s[0:1]
	v_add_u32_e32 v19, 0xb0, v146
	s_waitcnt lgkmcnt(0)
	v_mov_b64_e32 v[16:17], s[84:85]
	v_mad_i64_i32 v[16:17], s[12:13], v19, s94, v[16:17]
	v_lshl_add_u64 v[16:17], s[56:57], 1, v[16:17]
	v_fmamk_f32 v18, v18, 0x3a000000, v155
	v_mul_f32_e32 v20, 0x4b800000, v18
	v_cmp_gt_f32_e64 s[0:1], s93, v18
	s_nop 1
	v_cndmask_b32_e64 v18, v18, v20, s[0:1]
	v_rsq_f32_e32 v20, v18
	v_lshl_add_u64 v[18:19], v[16:17], 0, v[136:137]
	v_mul_f32_e32 v16, 0x45800000, v20
	v_cndmask_b32_e64 v16, v20, v16, s[0:1]
	v_pk_mul_f32 v[14:15], v[14:15], v[16:17] op_sel_hi:[1,0]
	v_pk_mul_f32 v[20:21], v[12:13], v[16:17] op_sel_hi:[1,0]
	v_pk_mul_f32 v[22:23], v[10:11], v[16:17] op_sel_hi:[1,0]
	v_pk_mul_f32 v[24:25], v[8:9], v[16:17] op_sel_hi:[1,0]
	v_pk_mul_f32 v[8:9], v[0:1], v[16:17] op_sel_hi:[1,0]
	v_cvt_pk_bf16_f32 v10, v20, v21
	v_cvt_pk_bf16_f32 v11, v14, v15
	v_cvt_pk_bf16_f32 v12, v24, v25
	v_cvt_pk_bf16_f32 v13, v22, v23
	v_mov_b32_e32 v1, v24
	v_mov_b32_e32 v24, v21
	v_mov_b32_e32 v21, v22
	v_mov_b32_e32 v22, v15
	v_mov_b32_e32 v0, v20
	v_mov_b32_e32 v20, v14
	global_store_dwordx4 v[18:19], v[10:13], off
	v_pk_mul_f32 v[6:7], v[6:7], v[16:17] op_sel_hi:[1,0]
	v_pk_mul_f32 v[4:5], v[4:5], v[16:17] op_sel_hi:[1,0]
	v_pk_mul_f32 v[10:11], v[24:25], v[24:25]
	v_pk_mul_f32 v[12:13], v[22:23], v[22:23]
	v_pk_fma_f32 v[0:1], v[0:1], v[0:1], v[10:11]
	v_pk_fma_f32 v[10:11], v[20:21], v[20:21], v[12:13]
	v_pk_mul_f32 v[2:3], v[2:3], v[16:17] op_sel_hi:[1,0]
	v_pk_add_f32 v[0:1], v[0:1], v[10:11]
	v_cvt_pk_bf16_f32 v14, v4, v5
	v_cvt_pk_bf16_f32 v15, v6, v7
	v_cvt_pk_bf16_f32 v16, v8, v9
	v_cvt_pk_bf16_f32 v17, v2, v3
	v_pk_add_f32 v[0:1], v[0:1], v[0:1] op_sel:[0,1] op_sel_hi:[1,0]
	global_store_dwordx4 v[18:19], v[14:17], off offset:256
	s_cbranch_vccnz .LBB0_608
	v_mov_b32_e32 v11, v8
	v_mov_b32_e32 v8, v5
	v_mov_b32_e32 v10, v4
	v_pk_mul_f32 v[4:5], v[8:9], v[8:9]
	v_mov_b32_e32 v9, v2
	v_mov_b32_e32 v2, v7
	v_mov_b32_e32 v8, v6
	v_pk_mul_f32 v[2:3], v[2:3], v[2:3]
	v_pk_fma_f32 v[4:5], v[10:11], v[10:11], v[4:5]
	v_pk_fma_f32 v[2:3], v[8:9], v[8:9], v[2:3]
	s_nop 0
	v_pk_add_f32 v[2:3], v[4:5], v[2:3]
	s_nop 0
	v_add_f32_e32 v1, v2, v3
	v_add_f32_e32 v0, v0, v1

.LBB0_685:
	s_lshl_b32 s51, s92, 8
	v_add_u32_e32 v246, s51, v177
	v_ashrrev_i32_e32 v247, 31, v246
	v_lshl_add_u64 v[246:247], v[246:247], 2, s[36:37]
	global_load_dword v238, v[246:247], off
	v_add_u32_e32 v246, s51, v195
	v_ashrrev_i32_e32 v247, 31, v246
	v_lshl_add_u64 v[246:247], v[246:247], 2, s[36:37]
	global_load_dword v239, v[246:247], off
	v_add_u32_e32 v246, s51, v197
	v_ashrrev_i32_e32 v247, 31, v246
	v_lshl_add_u64 v[246:247], v[246:247], 2, s[36:37]
	global_load_dword v240, v[246:247], off
	v_add_u32_e32 v246, s51, v199
	v_ashrrev_i32_e32 v247, 31, v246
	v_lshl_add_u64 v[246:247], v[246:247], 2, s[36:37]
	global_load_dword v241, v[246:247], off
	v_add_u32_e32 v246, s51, v201
	v_ashrrev_i32_e32 v247, 31, v246
	v_lshl_add_u64 v[246:247], v[246:247], 2, s[36:37]
	global_load_dword v242, v[246:247], off
	v_add_u32_e32 v246, s51, v203
	v_ashrrev_i32_e32 v247, 31, v246
	v_lshl_add_u64 v[246:247], v[246:247], 2, s[36:37]
	global_load_dword v243, v[246:247], off
	v_add_u32_e32 v246, s51, v205
	v_ashrrev_i32_e32 v247, 31, v246
	v_lshl_add_u64 v[246:247], v[246:247], 2, s[36:37]
	global_load_dword v244, v[246:247], off
	v_add_u32_e32 v246, s51, v207
	v_ashrrev_i32_e32 v247, 31, v246
	v_lshl_add_u64 v[246:247], v[246:247], 2, s[36:37]
	global_load_dword v245, v[246:247], off
	v_add_u32_e32 v166, s51, v177
	v_ashrrev_i32_e32 v167, 31, v166
	v_lshl_add_u64 v[156:157], v[166:167], 2, s[36:37]
	global_load_dword v150, v[156:157], off
	v_and_b32_e32 v152, 64, v213
	v_add_u32_e32 v159, 64, v152
	v_xor_b32_e32 v151, 16, v213
	v_cmp_lt_i32_e64 s[4:5], v151, v159
	s_waitcnt vmcnt(0)
	v_fmamk_f32 v150, v150, 0x3b000000, v215
	v_mul_f32_e32 v152, 0x4b800000, v150
	v_cmp_gt_f32_e32 vcc, s89, v150
	v_cndmask_b32_e64 v151, v213, v151, s[4:5]
	v_lshlrev_b32_e32 v158, 2, v151
	v_cndmask_b32_e32 v150, v150, v152, vcc
	v_rsq_f32_e32 v150, v150
	s_nop 0
	v_mul_f32_e32 v151, 0x45800000, v150
	v_cndmask_b32_e32 v150, v150, v151, vcc
	v_pk_mul_f32 v[152:153], v[126:127], v[150:151] op_sel_hi:[1,0]
	v_pk_mul_f32 v[154:155], v[124:125], v[150:151] op_sel_hi:[1,0]
	v_pk_mul_f32 v[160:161], v[122:123], v[150:151] op_sel_hi:[1,0]
	v_pk_mul_f32 v[150:151], v[120:121], v[150:151] op_sel_hi:[1,0]
	v_mul_f32_e32 v155, v155, v155
	v_mul_f32_e32 v153, v153, v153
	v_mul_f32_e32 v151, v151, v151
	v_mul_f32_e32 v161, v161, v161
	v_fmac_f32_e32 v155, v154, v154
	v_fmac_f32_e32 v153, v152, v152
	v_fmac_f32_e32 v151, v150, v150
	v_fmac_f32_e32 v161, v160, v160
	v_add_f32_e32 v150, v155, v153
	v_add_f32_e32 v151, v151, v161
	v_add_f32_e32 v150, v150, v151
	ds_bpermute_b32 v151, v158, v150
	v_xor_b32_e32 v152, 32, v213
	v_cmp_lt_i32_e32 vcc, v152, v159
	s_waitcnt lgkmcnt(0)
	v_add_f32_e32 v150, v150, v151
	v_cndmask_b32_e32 v152, v213, v152, vcc
	v_lshlrev_b32_e32 v159, 2, v152
	ds_bpermute_b32 v151, v159, v150
	s_and_saveexec_b64 s[4:5], s[8:9]
	s_cbranch_execz .LBB0_687
	s_waitcnt lgkmcnt(0)
	v_add_f32_e32 v150, v150, v151
	v_add_u32_e32 v151, s79, v194
	ds_write_b32 v151, v150
.LBB0_687:
	s_or_b64 exec, exec, s[4:5]
	v_add_u32_e32 v190, s51, v195
	v_ashrrev_i32_e32 v191, 31, v190
	v_lshl_add_u64 v[192:193], v[190:191], 2, s[36:37]
	v_mov_b32_e32 v150, v239
	v_fmamk_f32 v150, v150, 0x3b000000, v215
	s_waitcnt lgkmcnt(0)
	v_mul_f32_e32 v151, 0x4b800000, v150
	v_cmp_gt_f32_e32 vcc, s89, v150
	s_nop 1
	v_cndmask_b32_e32 v150, v150, v151, vcc
	v_rsq_f32_e32 v150, v150
	s_nop 0
	v_mul_f32_e32 v151, 0x45800000, v150
	v_cndmask_b32_e32 v150, v150, v151, vcc
	v_pk_mul_f32 v[152:153], v[110:111], v[150:151] op_sel_hi:[1,0]
	v_pk_mul_f32 v[154:155], v[108:109], v[150:151] op_sel_hi:[1,0]
	v_pk_mul_f32 v[160:161], v[106:107], v[150:151] op_sel_hi:[1,0]
	v_pk_mul_f32 v[150:151], v[104:105], v[150:151] op_sel_hi:[1,0]
	v_mul_f32_e32 v155, v155, v155
	v_mul_f32_e32 v153, v153, v153
	v_mul_f32_e32 v151, v151, v151
	v_mul_f32_e32 v161, v161, v161
	v_fmac_f32_e32 v155, v154, v154
	v_fmac_f32_e32 v153, v152, v152
	v_fmac_f32_e32 v151, v150, v150
	v_fmac_f32_e32 v161, v160, v160
	v_add_f32_e32 v150, v155, v153
	v_add_f32_e32 v151, v151, v161
	v_add_f32_e32 v150, v150, v151
	ds_bpermute_b32 v151, v158, v150
	s_waitcnt lgkmcnt(0)
	v_add_f32_e32 v150, v150, v151
	ds_bpermute_b32 v151, v159, v150
	s_and_saveexec_b64 s[4:5], s[8:9]
	s_cbranch_execz .LBB0_689
	s_waitcnt lgkmcnt(0)
	v_add_f32_e32 v150, v150, v151
	v_add_u32_e32 v151, s79, v196
	ds_write_b32 v151, v150
.LBB0_689:
	s_or_b64 exec, exec, s[4:5]
	v_add_u32_e32 v184, s51, v197
	v_ashrrev_i32_e32 v185, 31, v184
	v_lshl_add_u64 v[188:189], v[184:185], 2, s[36:37]
	v_mov_b32_e32 v150, v240
	v_fmamk_f32 v150, v150, 0x3b000000, v215
	s_waitcnt lgkmcnt(0)
	v_mul_f32_e32 v151, 0x4b800000, v150
	v_cmp_gt_f32_e32 vcc, s89, v150
	s_nop 1
	v_cndmask_b32_e32 v150, v150, v151, vcc
	v_rsq_f32_e32 v150, v150
	s_nop 0
	v_mul_f32_e32 v151, 0x45800000, v150
	v_cndmask_b32_e32 v150, v150, v151, vcc
	v_pk_mul_f32 v[152:153], v[94:95], v[150:151] op_sel_hi:[1,0]
	v_pk_mul_f32 v[154:155], v[92:93], v[150:151] op_sel_hi:[1,0]
	v_pk_mul_f32 v[160:161], v[90:91], v[150:151] op_sel_hi:[1,0]
	v_pk_mul_f32 v[150:151], v[88:89], v[150:151] op_sel_hi:[1,0]
	v_mul_f32_e32 v155, v155, v155
	v_mul_f32_e32 v153, v153, v153
	v_mul_f32_e32 v151, v151, v151
	v_mul_f32_e32 v161, v161, v161
	v_fmac_f32_e32 v155, v154, v154
	v_fmac_f32_e32 v153, v152, v152
	v_fmac_f32_e32 v151, v150, v150
	v_fmac_f32_e32 v161, v160, v160
	v_add_f32_e32 v150, v155, v153
	v_add_f32_e32 v151, v151, v161
	v_add_f32_e32 v150, v150, v151
	ds_bpermute_b32 v151, v158, v150
	s_waitcnt lgkmcnt(0)
	v_add_f32_e32 v150, v150, v151
	ds_bpermute_b32 v151, v159, v150
	s_and_saveexec_b64 s[4:5], s[8:9]
	s_cbranch_execz .LBB0_691
	s_waitcnt lgkmcnt(0)
	v_add_f32_e32 v150, v150, v151
	v_add_u32_e32 v151, s79, v198
	ds_write_b32 v151, v150
.LBB0_691:
	s_or_b64 exec, exec, s[4:5]
	v_add_u32_e32 v182, s51, v199
	v_ashrrev_i32_e32 v183, 31, v182
	v_lshl_add_u64 v[186:187], v[182:183], 2, s[36:37]
	v_mov_b32_e32 v150, v241
	v_fmamk_f32 v150, v150, 0x3b000000, v215
	s_waitcnt lgkmcnt(0)
	v_mul_f32_e32 v151, 0x4b800000, v150
	v_cmp_gt_f32_e32 vcc, s89, v150
	s_nop 1
	v_cndmask_b32_e32 v150, v150, v151, vcc
	v_rsq_f32_e32 v150, v150
	s_nop 0
	v_mul_f32_e32 v151, 0x45800000, v150
	v_cndmask_b32_e32 v150, v150, v151, vcc
	v_pk_mul_f32 v[152:153], v[78:79], v[150:151] op_sel_hi:[1,0]
	v_pk_mul_f32 v[154:155], v[76:77], v[150:151] op_sel_hi:[1,0]
	v_pk_mul_f32 v[160:161], v[74:75], v[150:151] op_sel_hi:[1,0]
	v_pk_mul_f32 v[150:151], v[72:73], v[150:151] op_sel_hi:[1,0]
	v_mul_f32_e32 v155, v155, v155
	v_mul_f32_e32 v153, v153, v153
	v_mul_f32_e32 v151, v151, v151
	v_mul_f32_e32 v161, v161, v161
	v_fmac_f32_e32 v155, v154, v154
	v_fmac_f32_e32 v153, v152, v152
	v_fmac_f32_e32 v151, v150, v150
	v_fmac_f32_e32 v161, v160, v160
	v_add_f32_e32 v150, v155, v153
	v_add_f32_e32 v151, v151, v161
	v_add_f32_e32 v150, v150, v151
	ds_bpermute_b32 v151, v158, v150
	s_waitcnt lgkmcnt(0)
	v_add_f32_e32 v150, v150, v151
	ds_bpermute_b32 v151, v159, v150
	s_and_saveexec_b64 s[4:5], s[8:9]
	s_cbranch_execz .LBB0_693
	s_waitcnt lgkmcnt(0)
	v_add_f32_e32 v150, v150, v151
	v_add_u32_e32 v151, s79, v200
	ds_write_b32 v151, v150
.LBB0_693:
	s_or_b64 exec, exec, s[4:5]
	v_add_u32_e32 v164, s51, v201
	v_ashrrev_i32_e32 v165, 31, v164
	v_lshl_add_u64 v[180:181], v[164:165], 2, s[36:37]
	v_mov_b32_e32 v150, v242
	v_fmamk_f32 v150, v150, 0x3b000000, v215
	s_waitcnt lgkmcnt(0)
	v_mul_f32_e32 v151, 0x4b800000, v150
	v_cmp_gt_f32_e32 vcc, s89, v150
	s_nop 1
	v_cndmask_b32_e32 v150, v150, v151, vcc
	v_rsq_f32_e32 v150, v150
	s_nop 0
	v_mul_f32_e32 v151, 0x45800000, v150
	v_cndmask_b32_e32 v150, v150, v151, vcc
	v_pk_mul_f32 v[152:153], v[62:63], v[150:151] op_sel_hi:[1,0]
	v_pk_mul_f32 v[154:155], v[60:61], v[150:151] op_sel_hi:[1,0]
	v_pk_mul_f32 v[160:161], v[58:59], v[150:151] op_sel_hi:[1,0]
	v_pk_mul_f32 v[150:151], v[56:57], v[150:151] op_sel_hi:[1,0]
	v_mul_f32_e32 v155, v155, v155
	v_mul_f32_e32 v153, v153, v153
	v_mul_f32_e32 v151, v151, v151
	v_mul_f32_e32 v161, v161, v161
	v_fmac_f32_e32 v155, v154, v154
	v_fmac_f32_e32 v153, v152, v152
	v_fmac_f32_e32 v151, v150, v150
	v_fmac_f32_e32 v161, v160, v160
	v_add_f32_e32 v150, v155, v153
	v_add_f32_e32 v151, v151, v161
	v_add_f32_e32 v150, v150, v151
	ds_bpermute_b32 v151, v158, v150
	s_waitcnt lgkmcnt(0)
	v_add_f32_e32 v150, v150, v151
	ds_bpermute_b32 v151, v159, v150
	s_and_saveexec_b64 s[4:5], s[8:9]
	s_cbranch_execz .LBB0_695
	s_waitcnt lgkmcnt(0)
	v_add_f32_e32 v150, v150, v151
	v_add_u32_e32 v151, s79, v202
	ds_write_b32 v151, v150
.LBB0_695:
	s_or_b64 exec, exec, s[4:5]
	v_add_u32_e32 v162, s51, v203
	v_ashrrev_i32_e32 v163, 31, v162
	v_lshl_add_u64 v[174:175], v[162:163], 2, s[36:37]
	v_mov_b32_e32 v150, v243
	v_fmamk_f32 v150, v150, 0x3b000000, v215
	s_waitcnt lgkmcnt(0)
	v_mul_f32_e32 v151, 0x4b800000, v150
	v_cmp_gt_f32_e32 vcc, s89, v150
	s_nop 1
	v_cndmask_b32_e32 v150, v150, v151, vcc
	v_rsq_f32_e32 v150, v150
	s_nop 0
	v_mul_f32_e32 v151, 0x45800000, v150
	v_cndmask_b32_e32 v150, v150, v151, vcc
	v_pk_mul_f32 v[152:153], v[46:47], v[150:151] op_sel_hi:[1,0]
	v_pk_mul_f32 v[154:155], v[44:45], v[150:151] op_sel_hi:[1,0]
	v_pk_mul_f32 v[160:161], v[42:43], v[150:151] op_sel_hi:[1,0]
	v_pk_mul_f32 v[150:151], v[40:41], v[150:151] op_sel_hi:[1,0]
	v_mul_f32_e32 v155, v155, v155
	v_mul_f32_e32 v153, v153, v153
	v_mul_f32_e32 v151, v151, v151
	v_mul_f32_e32 v161, v161, v161
	v_fmac_f32_e32 v155, v154, v154
	v_fmac_f32_e32 v153, v152, v152
	v_fmac_f32_e32 v151, v150, v150
	v_fmac_f32_e32 v161, v160, v160
	v_add_f32_e32 v150, v155, v153
	v_add_f32_e32 v151, v151, v161
	v_add_f32_e32 v150, v150, v151
	ds_bpermute_b32 v151, v158, v150
	s_waitcnt lgkmcnt(0)
	v_add_f32_e32 v150, v150, v151
	ds_bpermute_b32 v151, v159, v150
	s_and_saveexec_b64 s[4:5], s[8:9]
	s_cbranch_execz .LBB0_697
	s_waitcnt lgkmcnt(0)
	v_add_f32_e32 v150, v150, v151
	v_add_u32_e32 v151, s79, v204
	ds_write_b32 v151, v150
.LBB0_697:
	s_or_b64 exec, exec, s[4:5]
	v_add_u32_e32 v152, s51, v205
	v_ashrrev_i32_e32 v153, 31, v152
	v_lshl_add_u64 v[160:161], v[152:153], 2, s[36:37]
	v_mov_b32_e32 v150, v244
	v_fmamk_f32 v150, v150, 0x3b000000, v215
	s_waitcnt lgkmcnt(0)
	v_mul_f32_e32 v151, 0x4b800000, v150
	v_cmp_gt_f32_e32 vcc, s89, v150
	s_nop 1
	v_cndmask_b32_e32 v150, v150, v151, vcc
	v_rsq_f32_e32 v150, v150
	s_nop 0
	v_mul_f32_e32 v151, 0x45800000, v150
	v_cndmask_b32_e32 v150, v150, v151, vcc
	v_pk_mul_f32 v[154:155], v[30:31], v[150:151] op_sel_hi:[1,0]
	v_pk_mul_f32 v[168:169], v[28:29], v[150:151] op_sel_hi:[1,0]
	v_pk_mul_f32 v[170:171], v[26:27], v[150:151] op_sel_hi:[1,0]
	v_pk_mul_f32 v[150:151], v[24:25], v[150:151] op_sel_hi:[1,0]
	v_mul_f32_e32 v153, v169, v169
	v_mul_f32_e32 v155, v155, v155
	v_mul_f32_e32 v151, v151, v151
	v_mul_f32_e32 v163, v171, v171
	v_fmac_f32_e32 v153, v168, v168
	v_fmac_f32_e32 v155, v154, v154
	v_fmac_f32_e32 v151, v150, v150
	v_fmac_f32_e32 v163, v170, v170
	v_add_f32_e32 v150, v153, v155
	v_add_f32_e32 v151, v151, v163
	v_add_f32_e32 v150, v150, v151
	ds_bpermute_b32 v151, v158, v150
	s_waitcnt lgkmcnt(0)
	v_add_f32_e32 v150, v150, v151
	ds_bpermute_b32 v151, v159, v150
	s_and_saveexec_b64 s[4:5], s[8:9]
	s_cbranch_execz .LBB0_699
	s_waitcnt lgkmcnt(0)
	v_add_f32_e32 v150, v150, v151
	v_add_u32_e32 v151, s79, v206
	ds_write_b32 v151, v150
.LBB0_699:
	s_or_b64 exec, exec, s[4:5]
	v_add_u32_e32 v150, s51, v207
	s_waitcnt lgkmcnt(0)
	v_ashrrev_i32_e32 v151, 31, v150
	v_lshl_add_u64 v[154:155], v[150:151], 2, s[36:37]
	v_mov_b32_e32 v151, v245
	v_fmamk_f32 v151, v151, 0x3b000000, v215
	v_mul_f32_e32 v153, 0x4b800000, v151
	v_cmp_gt_f32_e32 vcc, s89, v151
	s_nop 1
	v_cndmask_b32_e32 v151, v151, v153, vcc
	v_rsq_f32_e32 v151, v151
	s_nop 0
	v_mul_f32_e32 v153, 0x45800000, v151
	v_cndmask_b32_e32 v168, v151, v153, vcc
	v_pk_mul_f32 v[170:171], v[14:15], v[168:169] op_sel_hi:[1,0]
	v_pk_mul_f32 v[172:173], v[12:13], v[168:169] op_sel_hi:[1,0]
	v_pk_mul_f32 v[216:217], v[10:11], v[168:169] op_sel_hi:[1,0]
	v_pk_mul_f32 v[168:169], v[8:9], v[168:169] op_sel_hi:[1,0]
	v_mul_f32_e32 v151, v173, v173
	v_mul_f32_e32 v153, v171, v171
	v_mul_f32_e32 v163, v169, v169
	v_mul_f32_e32 v165, v217, v217
	v_fmac_f32_e32 v151, v172, v172
	v_fmac_f32_e32 v153, v170, v170
	v_fmac_f32_e32 v163, v168, v168
	v_fmac_f32_e32 v165, v216, v216
	v_add_f32_e32 v151, v151, v153
	v_add_f32_e32 v153, v163, v165
	v_add_f32_e32 v151, v151, v153
	ds_bpermute_b32 v153, v158, v151
	s_waitcnt lgkmcnt(0)
	v_add_f32_e32 v151, v151, v153
	ds_bpermute_b32 v153, v159, v151
	s_and_saveexec_b64 s[4:5], s[8:9]
	s_cbranch_execz .LBB0_701
	s_waitcnt lgkmcnt(0)
	v_add_f32_e32 v151, v151, v153
	v_add_u32_e32 v153, s79, v209
	ds_write_b32 v153, v151
.LBB0_701:
	s_or_b64 exec, exec, s[4:5]
	s_waitcnt lgkmcnt(0)
	s_barrier
	global_load_dwordx4 v[168:171], v[138:139], off
	global_load_dwordx4 v[216:219], v[140:141], off
	v_mov_b32_e32 v172, v238
	global_load_dwordx4 v[220:223], v[138:139], off offset:16
	global_load_dwordx4 v[224:227], v[140:141], off offset:16
	s_add_i32 s51, 0, 0x21000
	v_add_u32_e32 v151, s51, v194
	ds_read_b128 v[228:231], v151
	s_lshl_b32 s4, s60, 8
	v_mov_b64_e32 v[158:159], s[10:11]
	s_ashr_i32 s5, s4, 31
	v_mad_i64_i32 v[166:167], s[56:57], v166, s90, v[158:159]
	s_lshl_b64 s[56:57], s[4:5], 1
	s_waitcnt lgkmcnt(1)
	v_add_u32_e32 v153, s51, v196
	v_lshl_add_u64 v[166:167], v[166:167], 0, s[56:57]
	ds_read_b128 v[232:235], v153
	v_lshl_add_u64 v[236:237], v[166:167], 0, v[136:137]
	s_waitcnt lgkmcnt(1)
	v_mov_b32_e32 v166, v229
	v_mov_b32_e32 v167, v230
	v_mov_b32_e32 v229, v231
	v_pk_add_f32 v[166:167], v[166:167], v[228:229]
	v_mov_b64_e32 v[156:157], s[48:49]
	v_pk_add_f32 v[166:167], v[166:167], v[166:167] op_sel_hi:[0,1]
	v_mov_b32_e32 v173, v167
	s_waitcnt vmcnt(2)
	v_pk_mul_f32 v[166:167], v[170:171], v[218:219]
	s_waitcnt vmcnt(2)
	v_pk_fma_f32 v[170:171], v[172:173], s[16:17], v[156:157] op_sel_hi:[1,1,0]
	v_pk_mul_f32 v[168:169], v[168:169], v[216:217]
	v_mul_f32_e32 v151, 0x4b800000, v170
	v_mul_f32_e32 v153, 0x4b800000, v171
	v_cmp_gt_f32_e32 vcc, s89, v170
	v_cmp_gt_f32_e64 s[4:5], s89, v171
	s_waitcnt vmcnt(0)
	v_pk_mul_f32 v[172:173], v[220:221], v[224:225]
	v_cndmask_b32_e32 v151, v170, v151, vcc
	v_cndmask_b32_e64 v153, v171, v153, s[4:5]
	v_rsq_f32_e32 v218, v151
	v_rsq_f32_e32 v219, v153
	v_pk_mul_f32 v[170:171], v[222:223], v[226:227]
	v_pk_mul_f32 v[216:217], v[218:219], s[46:47] op_sel_hi:[1,0]
	s_nop 0
	v_cndmask_b32_e64 v151, v219, v217, s[4:5]
	v_cndmask_b32_e32 v216, v218, v216, vcc
	v_mul_f32_e32 v218, v216, v151
	v_pk_mul_f32 v[118:119], v[118:119], v[216:217] op_sel_hi:[1,0]
	v_pk_mul_f32 v[116:117], v[116:117], v[216:217] op_sel_hi:[1,0]
	v_pk_mul_f32 v[220:221], v[114:115], v[216:217] op_sel_hi:[1,0]
	v_pk_mul_f32 v[114:115], v[112:113], v[216:217] op_sel_hi:[1,0]
	v_pk_mul_f32 v[124:125], v[124:125], v[218:219] op_sel_hi:[1,0]
	v_pk_mul_f32 v[126:127], v[126:127], v[218:219] op_sel_hi:[1,0]
	v_pk_mul_f32 v[120:121], v[120:121], v[218:219] op_sel_hi:[1,0]
	v_pk_mul_f32 v[122:123], v[122:123], v[218:219] op_sel_hi:[1,0]
	v_cvt_pk_bf16_f32 v112, v116, v117
	v_cvt_pk_bf16_f32 v113, v118, v119
	v_cvt_pk_bf16_f32 v114, v114, v115
	v_cvt_pk_bf16_f32 v115, v220, v221
	v_pk_mul_f32 v[116:117], v[166:167], v[126:127]
	v_pk_mul_f32 v[118:119], v[168:169], v[124:125]
	v_pk_mul_f32 v[122:123], v[170:171], v[122:123]
	v_pk_mul_f32 v[120:121], v[172:173], v[120:121]
	global_store_dwordx4 v[236:237], v[112:115], off offset:256
	s_nop 1
	v_cvt_pk_bf16_f32 v112, v118, v119
	v_cvt_pk_bf16_f32 v113, v116, v117
	v_cvt_pk_bf16_f32 v114, v120, v121
	v_cvt_pk_bf16_f32 v115, v122, v123
	global_store_dwordx4 v[236:237], v[112:115], off
	s_nop 1
	v_mov_b32_e32 v112, v239
	s_waitcnt lgkmcnt(0)
	v_mov_b32_e32 v114, v233
	v_mov_b32_e32 v115, v234
	v_mov_b32_e32 v233, v235
	v_pk_add_f32 v[114:115], v[114:115], v[232:233]
	s_nop 0
	v_pk_add_f32 v[114:115], v[114:115], v[114:115] op_sel_hi:[0,1]
	v_mov_b32_e32 v113, v115
	v_pk_fma_f32 v[112:113], v[112:113], s[16:17], v[156:157] op_sel_hi:[1,1,0]
	s_nop 0
	v_mul_f32_e32 v114, 0x4b800000, v112
	v_mul_f32_e32 v115, 0x4b800000, v113
	v_cmp_gt_f32_e32 vcc, s89, v112
	v_cmp_gt_f32_e64 s[4:5], s89, v113
	s_nop 0
	v_cndmask_b32_e32 v112, v112, v114, vcc
	v_cndmask_b32_e64 v113, v113, v115, s[4:5]
	v_rsq_f32_e32 v112, v112
	v_rsq_f32_e32 v113, v113
	v_mad_i64_i32 v[114:115], s[58:59], v190, s90, v[158:159]
	v_lshl_add_u64 v[114:115], v[114:115], 0, s[56:57]
	v_pk_mul_f32 v[116:117], v[112:113], s[46:47] op_sel_hi:[1,0]
	v_lshl_add_u64 v[114:115], v[114:115], 0, v[136:137]
	v_cndmask_b32_e64 v113, v113, v117, s[4:5]
	v_cndmask_b32_e32 v112, v112, v116, vcc
	v_mul_f32_e32 v116, v112, v113
	v_pk_mul_f32 v[102:103], v[102:103], v[112:113] op_sel_hi:[1,0]
	v_pk_mul_f32 v[100:101], v[100:101], v[112:113] op_sel_hi:[1,0]
	v_pk_mul_f32 v[118:119], v[98:99], v[112:113] op_sel_hi:[1,0]
	v_pk_mul_f32 v[98:99], v[96:97], v[112:113] op_sel_hi:[1,0]
	v_pk_mul_f32 v[108:109], v[108:109], v[116:117] op_sel_hi:[1,0]
	v_pk_mul_f32 v[110:111], v[110:111], v[116:117] op_sel_hi:[1,0]
	v_pk_mul_f32 v[104:105], v[104:105], v[116:117] op_sel_hi:[1,0]
	v_pk_mul_f32 v[106:107], v[106:107], v[116:117] op_sel_hi:[1,0]
	v_cvt_pk_bf16_f32 v96, v100, v101
	v_cvt_pk_bf16_f32 v97, v102, v103
	v_cvt_pk_bf16_f32 v98, v98, v99
	v_cvt_pk_bf16_f32 v99, v118, v119
	v_pk_mul_f32 v[100:101], v[166:167], v[110:111]
	v_pk_mul_f32 v[102:103], v[168:169], v[108:109]
	v_pk_mul_f32 v[106:107], v[170:171], v[106:107]
	v_pk_mul_f32 v[104:105], v[172:173], v[104:105]
	global_store_dwordx4 v[114:115], v[96:99], off offset:256
	s_nop 1
	v_cvt_pk_bf16_f32 v96, v102, v103
	v_cvt_pk_bf16_f32 v97, v100, v101
	v_cvt_pk_bf16_f32 v98, v104, v105
	v_cvt_pk_bf16_f32 v99, v106, v107
	global_store_dwordx4 v[114:115], v[96:99], off
	v_mov_b32_e32 v104, v240
	v_add_u32_e32 v100, s51, v200
	v_add_u32_e32 v96, s51, v198
	ds_read_b128 v[96:99], v96
	ds_read_b128 v[100:103], v100
	s_waitcnt lgkmcnt(1)
	v_mov_b32_e32 v106, v97
	v_mov_b32_e32 v107, v98
	v_mov_b32_e32 v97, v99
	v_pk_add_f32 v[96:97], v[106:107], v[96:97]
	s_nop 0
	v_pk_add_f32 v[96:97], v[96:97], v[96:97] op_sel_hi:[0,1]
	v_mov_b32_e32 v105, v97
	v_pk_fma_f32 v[96:97], v[104:105], s[16:17], v[156:157] op_sel_hi:[1,1,0]
	s_nop 0
	v_mul_f32_e32 v98, 0x4b800000, v96
	v_mul_f32_e32 v99, 0x4b800000, v97
	v_cmp_gt_f32_e32 vcc, s89, v96
	v_cmp_gt_f32_e64 s[4:5], s89, v97
	s_nop 0
	v_cndmask_b32_e32 v96, v96, v98, vcc
	v_cndmask_b32_e64 v97, v97, v99, s[4:5]
	v_rsq_f32_e32 v96, v96
	v_rsq_f32_e32 v97, v97
	v_mad_i64_i32 v[98:99], s[58:59], v184, s90, v[158:159]
	v_lshl_add_u64 v[98:99], v[98:99], 0, s[56:57]
	v_pk_mul_f32 v[104:105], v[96:97], s[46:47] op_sel_hi:[1,0]
	v_lshl_add_u64 v[98:99], v[98:99], 0, v[136:137]
	v_cndmask_b32_e64 v97, v97, v105, s[4:5]
	v_cndmask_b32_e32 v96, v96, v104, vcc
	v_mul_f32_e32 v104, v96, v97
	v_pk_mul_f32 v[86:87], v[86:87], v[96:97] op_sel_hi:[1,0]
	v_pk_mul_f32 v[84:85], v[84:85], v[96:97] op_sel_hi:[1,0]
	v_pk_mul_f32 v[106:107], v[82:83], v[96:97] op_sel_hi:[1,0]
	v_pk_mul_f32 v[82:83], v[80:81], v[96:97] op_sel_hi:[1,0]
	v_pk_mul_f32 v[92:93], v[92:93], v[104:105] op_sel_hi:[1,0]
	v_pk_mul_f32 v[94:95], v[94:95], v[104:105] op_sel_hi:[1,0]
	v_pk_mul_f32 v[88:89], v[88:89], v[104:105] op_sel_hi:[1,0]
	v_pk_mul_f32 v[90:91], v[90:91], v[104:105] op_sel_hi:[1,0]
	v_cvt_pk_bf16_f32 v80, v84, v85
	v_cvt_pk_bf16_f32 v81, v86, v87
	v_cvt_pk_bf16_f32 v82, v82, v83
	v_cvt_pk_bf16_f32 v83, v106, v107
	v_pk_mul_f32 v[84:85], v[166:167], v[94:95]
	v_pk_mul_f32 v[86:87], v[168:169], v[92:93]
	v_pk_mul_f32 v[90:91], v[170:171], v[90:91]
	v_pk_mul_f32 v[88:89], v[172:173], v[88:89]
	global_store_dwordx4 v[98:99], v[80:83], off offset:256
	s_nop 1
	v_cvt_pk_bf16_f32 v80, v86, v87
	v_cvt_pk_bf16_f32 v81, v84, v85
	v_cvt_pk_bf16_f32 v82, v88, v89
	v_cvt_pk_bf16_f32 v83, v90, v91
	global_store_dwordx4 v[98:99], v[80:83], off
	s_nop 1
	v_mov_b32_e32 v80, v241
	s_waitcnt lgkmcnt(0)
	v_mov_b32_e32 v82, v101
	v_mov_b32_e32 v83, v102
	v_mov_b32_e32 v101, v103
	v_pk_add_f32 v[82:83], v[82:83], v[100:101]
	s_nop 0
	v_pk_add_f32 v[82:83], v[82:83], v[82:83] op_sel_hi:[0,1]
	v_mov_b32_e32 v81, v83
	v_pk_fma_f32 v[80:81], v[80:81], s[16:17], v[156:157] op_sel_hi:[1,1,0]
	s_nop 0
	v_mul_f32_e32 v82, 0x4b800000, v80
	v_mul_f32_e32 v83, 0x4b800000, v81
	v_cmp_gt_f32_e32 vcc, s89, v80
	v_cmp_gt_f32_e64 s[4:5], s89, v81
	s_nop 0
	v_cndmask_b32_e32 v80, v80, v82, vcc
	v_cndmask_b32_e64 v81, v81, v83, s[4:5]
	v_rsq_f32_e32 v80, v80
	v_rsq_f32_e32 v81, v81
	v_mad_i64_i32 v[82:83], s[58:59], v182, s90, v[158:159]
	v_lshl_add_u64 v[82:83], v[82:83], 0, s[56:57]
	v_pk_mul_f32 v[84:85], v[80:81], s[46:47] op_sel_hi:[1,0]
	v_lshl_add_u64 v[82:83], v[82:83], 0, v[136:137]
	v_cndmask_b32_e64 v81, v81, v85, s[4:5]
	v_cndmask_b32_e32 v80, v80, v84, vcc
	v_mul_f32_e32 v84, v80, v81
	v_pk_mul_f32 v[70:71], v[70:71], v[80:81] op_sel_hi:[1,0]
	v_pk_mul_f32 v[68:69], v[68:69], v[80:81] op_sel_hi:[1,0]
	v_pk_mul_f32 v[86:87], v[66:67], v[80:81] op_sel_hi:[1,0]
	v_pk_mul_f32 v[66:67], v[64:65], v[80:81] op_sel_hi:[1,0]
	v_pk_mul_f32 v[76:77], v[76:77], v[84:85] op_sel_hi:[1,0]
	v_pk_mul_f32 v[78:79], v[78:79], v[84:85] op_sel_hi:[1,0]
	v_pk_mul_f32 v[72:73], v[72:73], v[84:85] op_sel_hi:[1,0]
	v_pk_mul_f32 v[74:75], v[74:75], v[84:85] op_sel_hi:[1,0]
	v_cvt_pk_bf16_f32 v64, v68, v69
	v_cvt_pk_bf16_f32 v65, v70, v71
	v_cvt_pk_bf16_f32 v66, v66, v67
	v_cvt_pk_bf16_f32 v67, v86, v87
	v_pk_mul_f32 v[68:69], v[166:167], v[78:79]
	v_pk_mul_f32 v[70:71], v[168:169], v[76:77]
	v_pk_mul_f32 v[74:75], v[170:171], v[74:75]
	v_pk_mul_f32 v[72:73], v[172:173], v[72:73]
	global_store_dwordx4 v[82:83], v[64:67], off offset:256
	s_nop 1
	v_cvt_pk_bf16_f32 v64, v70, v71
	v_cvt_pk_bf16_f32 v65, v68, v69
	v_cvt_pk_bf16_f32 v66, v72, v73
	v_cvt_pk_bf16_f32 v67, v74, v75
	global_store_dwordx4 v[82:83], v[64:67], off
	v_mov_b32_e32 v72, v242
	v_add_u32_e32 v68, s51, v204
	v_add_u32_e32 v64, s51, v202
	ds_read_b128 v[64:67], v64
	ds_read_b128 v[68:71], v68
	s_waitcnt lgkmcnt(1)
	v_mov_b32_e32 v74, v65
	v_mov_b32_e32 v75, v66
	v_mov_b32_e32 v65, v67
	v_pk_add_f32 v[64:65], v[74:75], v[64:65]
	s_nop 0
	v_pk_add_f32 v[64:65], v[64:65], v[64:65] op_sel_hi:[0,1]
	v_mov_b32_e32 v73, v65
	v_pk_fma_f32 v[64:65], v[72:73], s[16:17], v[156:157] op_sel_hi:[1,1,0]
	s_nop 0
	v_mul_f32_e32 v66, 0x4b800000, v64
	v_mul_f32_e32 v67, 0x4b800000, v65
	v_cmp_gt_f32_e32 vcc, s89, v64
	v_cmp_gt_f32_e64 s[4:5], s89, v65
	s_nop 0
	v_cndmask_b32_e32 v64, v64, v66, vcc
	v_cndmask_b32_e64 v65, v65, v67, s[4:5]
	v_rsq_f32_e32 v64, v64
	v_rsq_f32_e32 v65, v65
	v_mad_i64_i32 v[66:67], s[58:59], v164, s90, v[158:159]
	v_lshl_add_u64 v[66:67], v[66:67], 0, s[56:57]
	v_pk_mul_f32 v[72:73], v[64:65], s[46:47] op_sel_hi:[1,0]
	v_lshl_add_u64 v[66:67], v[66:67], 0, v[136:137]
	v_cndmask_b32_e64 v65, v65, v73, s[4:5]
	v_cndmask_b32_e32 v64, v64, v72, vcc
	v_mul_f32_e32 v72, v64, v65
	v_pk_mul_f32 v[54:55], v[54:55], v[64:65] op_sel_hi:[1,0]
	v_pk_mul_f32 v[52:53], v[52:53], v[64:65] op_sel_hi:[1,0]
	v_pk_mul_f32 v[74:75], v[50:51], v[64:65] op_sel_hi:[1,0]
	v_pk_mul_f32 v[50:51], v[48:49], v[64:65] op_sel_hi:[1,0]
	v_pk_mul_f32 v[60:61], v[60:61], v[72:73] op_sel_hi:[1,0]
	v_pk_mul_f32 v[62:63], v[62:63], v[72:73] op_sel_hi:[1,0]
	v_pk_mul_f32 v[56:57], v[56:57], v[72:73] op_sel_hi:[1,0]
	v_pk_mul_f32 v[58:59], v[58:59], v[72:73] op_sel_hi:[1,0]
	v_cvt_pk_bf16_f32 v48, v52, v53
	v_cvt_pk_bf16_f32 v49, v54, v55
	v_cvt_pk_bf16_f32 v50, v50, v51
	v_cvt_pk_bf16_f32 v51, v74, v75
	v_pk_mul_f32 v[52:53], v[166:167], v[62:63]
	v_pk_mul_f32 v[54:55], v[168:169], v[60:61]
	v_pk_mul_f32 v[58:59], v[170:171], v[58:59]
	v_pk_mul_f32 v[56:57], v[172:173], v[56:57]
	global_store_dwordx4 v[66:67], v[48:51], off offset:256
	s_nop 1
	v_cvt_pk_bf16_f32 v48, v54, v55
	v_cvt_pk_bf16_f32 v49, v52, v53
	v_cvt_pk_bf16_f32 v50, v56, v57
	v_cvt_pk_bf16_f32 v51, v58, v59
	global_store_dwordx4 v[66:67], v[48:51], off
	s_nop 1
	v_mov_b32_e32 v48, v243
	s_waitcnt lgkmcnt(0)
	v_mov_b32_e32 v50, v69
	v_mov_b32_e32 v51, v70
	v_mov_b32_e32 v69, v71
	v_pk_add_f32 v[50:51], v[50:51], v[68:69]
	s_nop 0
	v_pk_add_f32 v[50:51], v[50:51], v[50:51] op_sel_hi:[0,1]
	v_mov_b32_e32 v49, v51
	v_pk_fma_f32 v[48:49], v[48:49], s[16:17], v[156:157] op_sel_hi:[1,1,0]
	s_nop 0
	v_mul_f32_e32 v50, 0x4b800000, v48
	v_mul_f32_e32 v51, 0x4b800000, v49
	v_cmp_gt_f32_e32 vcc, s89, v48
	v_cmp_gt_f32_e64 s[4:5], s89, v49
	s_nop 0
	v_cndmask_b32_e32 v48, v48, v50, vcc
	v_cndmask_b32_e64 v49, v49, v51, s[4:5]
	v_rsq_f32_e32 v48, v48
	v_rsq_f32_e32 v49, v49
	v_mad_i64_i32 v[50:51], s[58:59], v162, s90, v[158:159]
	v_lshl_add_u64 v[50:51], v[50:51], 0, s[56:57]
	v_pk_mul_f32 v[52:53], v[48:49], s[46:47] op_sel_hi:[1,0]
	v_lshl_add_u64 v[50:51], v[50:51], 0, v[136:137]
	v_cndmask_b32_e64 v49, v49, v53, s[4:5]
	v_cndmask_b32_e32 v48, v48, v52, vcc
	v_mul_f32_e32 v52, v48, v49
	v_pk_mul_f32 v[38:39], v[38:39], v[48:49] op_sel_hi:[1,0]
	v_pk_mul_f32 v[36:37], v[36:37], v[48:49] op_sel_hi:[1,0]
	v_pk_mul_f32 v[54:55], v[34:35], v[48:49] op_sel_hi:[1,0]
	v_pk_mul_f32 v[34:35], v[32:33], v[48:49] op_sel_hi:[1,0]
	v_pk_mul_f32 v[44:45], v[44:45], v[52:53] op_sel_hi:[1,0]
	v_pk_mul_f32 v[46:47], v[46:47], v[52:53] op_sel_hi:[1,0]
	v_pk_mul_f32 v[40:41], v[40:41], v[52:53] op_sel_hi:[1,0]
	v_pk_mul_f32 v[42:43], v[42:43], v[52:53] op_sel_hi:[1,0]
	v_cvt_pk_bf16_f32 v32, v36, v37
	v_cvt_pk_bf16_f32 v33, v38, v39
	v_cvt_pk_bf16_f32 v34, v34, v35
	v_cvt_pk_bf16_f32 v35, v54, v55
	v_pk_mul_f32 v[36:37], v[166:167], v[46:47]
	v_pk_mul_f32 v[38:39], v[168:169], v[44:45]
	v_pk_mul_f32 v[42:43], v[170:171], v[42:43]
	v_pk_mul_f32 v[40:41], v[172:173], v[40:41]
	global_store_dwordx4 v[50:51], v[32:35], off offset:256
	s_nop 1
	v_cvt_pk_bf16_f32 v32, v38, v39
	v_cvt_pk_bf16_f32 v33, v36, v37
	v_cvt_pk_bf16_f32 v34, v40, v41
	v_cvt_pk_bf16_f32 v35, v42, v43
	global_store_dwordx4 v[50:51], v[32:35], off
	v_mov_b32_e32 v40, v244
	v_add_u32_e32 v36, s51, v209
	v_add_u32_e32 v32, s51, v206
	ds_read_b128 v[32:35], v32
	ds_read_b128 v[36:39], v36
	s_waitcnt lgkmcnt(1)
	v_mov_b32_e32 v42, v33
	v_mov_b32_e32 v43, v34
	v_mov_b32_e32 v33, v35
	v_pk_add_f32 v[32:33], v[42:43], v[32:33]
	s_nop 0
	v_pk_add_f32 v[32:33], v[32:33], v[32:33] op_sel_hi:[0,1]
	v_mov_b32_e32 v41, v33
	v_pk_fma_f32 v[32:33], v[40:41], s[16:17], v[156:157] op_sel_hi:[1,1,0]
	s_nop 0
	v_mul_f32_e32 v34, 0x4b800000, v32
	v_mul_f32_e32 v35, 0x4b800000, v33
	v_cmp_gt_f32_e32 vcc, s89, v32
	v_cmp_gt_f32_e64 s[4:5], s89, v33
	s_nop 0
	v_cndmask_b32_e32 v32, v32, v34, vcc
	v_cndmask_b32_e64 v33, v33, v35, s[4:5]
	v_rsq_f32_e32 v32, v32
	v_rsq_f32_e32 v33, v33
	v_mad_i64_i32 v[34:35], s[58:59], v152, s90, v[158:159]
	v_lshl_add_u64 v[34:35], v[34:35], 0, s[56:57]
	v_pk_mul_f32 v[40:41], v[32:33], s[46:47] op_sel_hi:[1,0]
	v_lshl_add_u64 v[34:35], v[34:35], 0, v[136:137]
	v_cndmask_b32_e64 v33, v33, v41, s[4:5]
	v_cndmask_b32_e32 v32, v32, v40, vcc
	v_mul_f32_e32 v40, v32, v33
	v_pk_mul_f32 v[22:23], v[22:23], v[32:33] op_sel_hi:[1,0]
	v_pk_mul_f32 v[20:21], v[20:21], v[32:33] op_sel_hi:[1,0]
	v_pk_mul_f32 v[42:43], v[18:19], v[32:33] op_sel_hi:[1,0]
	v_pk_mul_f32 v[18:19], v[16:17], v[32:33] op_sel_hi:[1,0]
	v_pk_mul_f32 v[28:29], v[28:29], v[40:41] op_sel_hi:[1,0]
	v_pk_mul_f32 v[30:31], v[30:31], v[40:41] op_sel_hi:[1,0]
	v_pk_mul_f32 v[24:25], v[24:25], v[40:41] op_sel_hi:[1,0]
	v_pk_mul_f32 v[26:27], v[26:27], v[40:41] op_sel_hi:[1,0]
	v_cvt_pk_bf16_f32 v16, v20, v21
	v_cvt_pk_bf16_f32 v17, v22, v23
	v_cvt_pk_bf16_f32 v18, v18, v19
	v_cvt_pk_bf16_f32 v19, v42, v43
	v_pk_mul_f32 v[20:21], v[166:167], v[30:31]
	v_pk_mul_f32 v[22:23], v[168:169], v[28:29]
	v_pk_mul_f32 v[26:27], v[170:171], v[26:27]
	v_pk_mul_f32 v[24:25], v[172:173], v[24:25]
	global_store_dwordx4 v[34:35], v[16:19], off offset:256
	s_and_b64 vcc, exec, s[0:1]
	s_nop 0
	v_cvt_pk_bf16_f32 v16, v22, v23
	v_cvt_pk_bf16_f32 v17, v20, v21
	v_cvt_pk_bf16_f32 v18, v24, v25
	v_cvt_pk_bf16_f32 v19, v26, v27
	global_store_dwordx4 v[34:35], v[16:19], off
	s_nop 1
	v_mov_b32_e32 v16, v245
	s_waitcnt lgkmcnt(0)
	v_mov_b32_e32 v18, v37
	v_mov_b32_e32 v19, v38
	v_mov_b32_e32 v37, v39
	v_pk_add_f32 v[18:19], v[18:19], v[36:37]
	s_nop 0
	v_pk_add_f32 v[18:19], v[18:19], v[18:19] op_sel_hi:[0,1]
	v_mov_b32_e32 v17, v19
	v_pk_fma_f32 v[16:17], v[16:17], s[16:17], v[156:157] op_sel_hi:[1,1,0]
	s_nop 0
	v_mul_f32_e32 v18, 0x4b800000, v16
	v_mul_f32_e32 v19, 0x4b800000, v17
	v_cmp_gt_f32_e64 s[0:1], s89, v16
	v_cmp_gt_f32_e64 s[4:5], s89, v17
	s_nop 0
	v_cndmask_b32_e64 v16, v16, v18, s[0:1]
	v_cndmask_b32_e64 v17, v17, v19, s[4:5]
	v_rsq_f32_e32 v16, v16
	v_rsq_f32_e32 v17, v17
	v_mad_i64_i32 v[18:19], s[58:59], v150, s90, v[158:159]
	v_lshl_add_u64 v[18:19], v[18:19], 0, s[56:57]
	v_pk_mul_f32 v[20:21], v[16:17], s[46:47] op_sel_hi:[1,0]
	v_lshl_add_u64 v[18:19], v[18:19], 0, v[136:137]
	v_cndmask_b32_e64 v17, v17, v21, s[4:5]
	v_cndmask_b32_e64 v16, v16, v20, s[0:1]
	v_mul_f32_e32 v20, v16, v17
	v_pk_mul_f32 v[6:7], v[6:7], v[16:17] op_sel_hi:[1,0]
	v_pk_mul_f32 v[4:5], v[4:5], v[16:17] op_sel_hi:[1,0]
	v_pk_mul_f32 v[22:23], v[2:3], v[16:17] op_sel_hi:[1,0]
	v_pk_mul_f32 v[2:3], v[0:1], v[16:17] op_sel_hi:[1,0]
	v_pk_mul_f32 v[12:13], v[12:13], v[20:21] op_sel_hi:[1,0]
	v_pk_mul_f32 v[14:15], v[14:15], v[20:21] op_sel_hi:[1,0]
	v_pk_mul_f32 v[8:9], v[8:9], v[20:21] op_sel_hi:[1,0]
	v_pk_mul_f32 v[10:11], v[10:11], v[20:21] op_sel_hi:[1,0]
	v_cvt_pk_bf16_f32 v0, v4, v5
	v_cvt_pk_bf16_f32 v1, v6, v7
	v_cvt_pk_bf16_f32 v2, v2, v3
	v_cvt_pk_bf16_f32 v3, v22, v23
	v_pk_mul_f32 v[4:5], v[166:167], v[14:15]
	v_pk_mul_f32 v[6:7], v[168:169], v[12:13]
	v_pk_mul_f32 v[10:11], v[170:171], v[10:11]
	v_pk_mul_f32 v[8:9], v[172:173], v[8:9]
	global_store_dwordx4 v[18:19], v[0:3], off offset:256
	s_mov_b64 s[0:1], -1
	s_nop 0
	v_cvt_pk_bf16_f32 v0, v6, v7
	v_cvt_pk_bf16_f32 v1, v4, v5
	v_cvt_pk_bf16_f32 v2, v8, v9
	v_cvt_pk_bf16_f32 v3, v10, v11
	global_store_dwordx4 v[18:19], v[0:3], off
	s_cbranch_vccnz .LBB0_676
	s_andn2_b64 vcc, exec, s[38:39]
	s_cbranch_vccnz .LBB0_675
	s_barrier
	s_branch .LBB0_675

.LBB0_719:
	v_lshl_add_u32 v146, s78, 8, v152
	v_ashrrev_i32_e32 v147, 31, v146
	v_lshl_add_u64 v[150:151], v[146:147], 2, s[28:29]
	global_load_dword v147, v[150:151], off
	global_load_dword v237, v[150:151], off offset:64
	global_load_dword v238, v[150:151], off offset:128
	global_load_dword v239, v[150:151], off offset:192
	global_load_dword v240, v[150:151], off offset:512
	global_load_dword v241, v[150:151], off offset:576
	global_load_dword v242, v[150:151], off offset:640
	global_load_dword v243, v[150:151], off offset:704
	v_or_b32_e32 v160, 16, v146
	s_lshl_b32 s4, s79, 8
	v_ashrrev_i32_e32 v161, 31, v160
	v_mov_b64_e32 v[148:149], s[8:9]
	s_ashr_i32 s5, s4, 31
	v_mad_i64_i32 v[158:159], s[48:49], v146, s74, v[148:149]
	s_lshl_b64 s[4:5], s[4:5], 1
	v_lshl_add_u64 v[158:159], v[158:159], 0, s[4:5]
	v_lshl_add_u64 v[158:159], v[158:159], 0, v[136:137]
	s_waitcnt vmcnt(0)
	v_fmamk_f32 v147, v147, 0x3b000000, v157
	v_mul_f32_e32 v162, 0x4b800000, v147
	v_cmp_gt_f32_e32 vcc, s67, v147
	s_nop 1
	v_cndmask_b32_e32 v147, v147, v162, vcc
	v_rsq_f32_e32 v147, v147
	v_lshl_add_u64 v[162:163], v[160:161], 2, s[28:29]
	v_mul_f32_e32 v161, 0x45800000, v147
	v_cndmask_b32_e32 v164, v147, v161, vcc
	v_pk_mul_f32 v[126:127], v[126:127], v[164:165] op_sel_hi:[1,0]
	v_pk_mul_f32 v[124:125], v[124:125], v[164:165] op_sel_hi:[1,0]
	v_pk_mul_f32 v[122:123], v[122:123], v[164:165] op_sel_hi:[1,0]
	v_pk_mul_f32 v[120:121], v[120:121], v[164:165] op_sel_hi:[1,0]
	v_pk_mul_f32 v[118:119], v[118:119], v[164:165] op_sel_hi:[1,0]
	v_pk_mul_f32 v[116:117], v[116:117], v[164:165] op_sel_hi:[1,0]
	v_pk_mul_f32 v[166:167], v[114:115], v[164:165] op_sel_hi:[1,0]
	v_pk_mul_f32 v[164:165], v[112:113], v[164:165] op_sel_hi:[1,0]
	v_cvt_pk_bf16_f32 v112, v124, v125
	v_cvt_pk_bf16_f32 v113, v126, v127
	v_cvt_pk_bf16_f32 v114, v120, v121
	v_cvt_pk_bf16_f32 v115, v122, v123
	v_cvt_pk_bf16_f32 v116, v116, v117
	v_cvt_pk_bf16_f32 v117, v118, v119
	v_cvt_pk_bf16_f32 v118, v164, v165
	v_cvt_pk_bf16_f32 v119, v166, v167
	global_store_dwordx4 v[158:159], v[112:115], off
	global_store_dwordx4 v[158:159], v[116:119], off offset:256
	s_nop 1
	v_mov_b32_e32 v116, v237
	v_or_b32_e32 v112, 32, v146
	v_ashrrev_i32_e32 v113, 31, v112
	v_mad_i64_i32 v[114:115], s[48:49], v160, s74, v[148:149]
	v_lshl_add_u64 v[114:115], v[114:115], 0, s[4:5]
	v_lshl_add_u64 v[114:115], v[114:115], 0, v[136:137]
	v_fmamk_f32 v116, v116, 0x3b000000, v157
	v_mul_f32_e32 v117, 0x4b800000, v116
	v_cmp_gt_f32_e32 vcc, s67, v116
	s_nop 1
	v_cndmask_b32_e32 v116, v116, v117, vcc
	v_rsq_f32_e32 v118, v116
	v_lshl_add_u64 v[116:117], v[112:113], 2, s[28:29]
	v_mul_f32_e32 v113, 0x45800000, v118
	v_cndmask_b32_e32 v118, v118, v113, vcc
	v_pk_mul_f32 v[110:111], v[110:111], v[118:119] op_sel_hi:[1,0]
	v_pk_mul_f32 v[108:109], v[108:109], v[118:119] op_sel_hi:[1,0]
	v_pk_mul_f32 v[106:107], v[106:107], v[118:119] op_sel_hi:[1,0]
	v_pk_mul_f32 v[104:105], v[104:105], v[118:119] op_sel_hi:[1,0]
	v_pk_mul_f32 v[102:103], v[102:103], v[118:119] op_sel_hi:[1,0]
	v_pk_mul_f32 v[100:101], v[100:101], v[118:119] op_sel_hi:[1,0]
	v_pk_mul_f32 v[120:121], v[98:99], v[118:119] op_sel_hi:[1,0]
	v_pk_mul_f32 v[118:119], v[96:97], v[118:119] op_sel_hi:[1,0]
	v_cvt_pk_bf16_f32 v96, v108, v109
	v_cvt_pk_bf16_f32 v97, v110, v111
	v_cvt_pk_bf16_f32 v98, v104, v105
	v_cvt_pk_bf16_f32 v99, v106, v107
	v_cvt_pk_bf16_f32 v100, v100, v101
	v_cvt_pk_bf16_f32 v101, v102, v103
	v_cvt_pk_bf16_f32 v102, v118, v119
	v_cvt_pk_bf16_f32 v103, v120, v121
	global_store_dwordx4 v[114:115], v[96:99], off
	global_store_dwordx4 v[114:115], v[100:103], off offset:256
	s_nop 1
	v_mov_b32_e32 v100, v238
	v_or_b32_e32 v96, 48, v146
	v_ashrrev_i32_e32 v97, 31, v96
	v_mad_i64_i32 v[98:99], s[48:49], v112, s74, v[148:149]
	v_lshl_add_u64 v[98:99], v[98:99], 0, s[4:5]
	v_lshl_add_u64 v[98:99], v[98:99], 0, v[136:137]
	v_fmamk_f32 v100, v100, 0x3b000000, v157
	v_mul_f32_e32 v101, 0x4b800000, v100
	v_cmp_gt_f32_e32 vcc, s67, v100
	s_nop 1
	v_cndmask_b32_e32 v100, v100, v101, vcc
	v_rsq_f32_e32 v102, v100
	v_lshl_add_u64 v[100:101], v[96:97], 2, s[28:29]
	v_mul_f32_e32 v97, 0x45800000, v102
	v_cndmask_b32_e32 v102, v102, v97, vcc
	v_pk_mul_f32 v[94:95], v[94:95], v[102:103] op_sel_hi:[1,0]
	v_pk_mul_f32 v[92:93], v[92:93], v[102:103] op_sel_hi:[1,0]
	v_pk_mul_f32 v[90:91], v[90:91], v[102:103] op_sel_hi:[1,0]
	v_pk_mul_f32 v[88:89], v[88:89], v[102:103] op_sel_hi:[1,0]
	v_pk_mul_f32 v[86:87], v[86:87], v[102:103] op_sel_hi:[1,0]
	v_pk_mul_f32 v[84:85], v[84:85], v[102:103] op_sel_hi:[1,0]
	v_pk_mul_f32 v[104:105], v[82:83], v[102:103] op_sel_hi:[1,0]
	v_pk_mul_f32 v[102:103], v[80:81], v[102:103] op_sel_hi:[1,0]
	v_cvt_pk_bf16_f32 v80, v92, v93
	v_cvt_pk_bf16_f32 v81, v94, v95
	v_cvt_pk_bf16_f32 v82, v88, v89
	v_cvt_pk_bf16_f32 v83, v90, v91
	v_cvt_pk_bf16_f32 v84, v84, v85
	v_cvt_pk_bf16_f32 v85, v86, v87
	v_cvt_pk_bf16_f32 v86, v102, v103
	v_cvt_pk_bf16_f32 v87, v104, v105
	global_store_dwordx4 v[98:99], v[80:83], off
	global_store_dwordx4 v[98:99], v[84:87], off offset:256
	s_nop 0
	v_mov_b32_e32 v80, v239
	v_fmamk_f32 v80, v80, 0x3b000000, v157
	v_mul_f32_e32 v81, 0x4b800000, v80
	v_cmp_gt_f32_e32 vcc, s67, v80
	s_nop 1
	v_cndmask_b32_e32 v80, v80, v81, vcc
	v_rsq_f32_e32 v82, v80
	v_mad_i64_i32 v[80:81], s[48:49], v96, s74, v[148:149]
	v_lshl_add_u64 v[80:81], v[80:81], 0, s[4:5]
	v_mul_f32_e32 v83, 0x45800000, v82
	v_cndmask_b32_e32 v82, v82, v83, vcc
	v_pk_mul_f32 v[78:79], v[78:79], v[82:83] op_sel_hi:[1,0]
	v_pk_mul_f32 v[76:77], v[76:77], v[82:83] op_sel_hi:[1,0]
	v_pk_mul_f32 v[74:75], v[74:75], v[82:83] op_sel_hi:[1,0]
	v_pk_mul_f32 v[72:73], v[72:73], v[82:83] op_sel_hi:[1,0]
	v_lshl_add_u64 v[80:81], v[80:81], 0, v[136:137]
	v_pk_mul_f32 v[70:71], v[70:71], v[82:83] op_sel_hi:[1,0]
	v_pk_mul_f32 v[68:69], v[68:69], v[82:83] op_sel_hi:[1,0]
	v_pk_mul_f32 v[84:85], v[66:67], v[82:83] op_sel_hi:[1,0]
	v_pk_mul_f32 v[82:83], v[64:65], v[82:83] op_sel_hi:[1,0]
	v_cvt_pk_bf16_f32 v64, v76, v77
	v_cvt_pk_bf16_f32 v65, v78, v79
	v_cvt_pk_bf16_f32 v66, v72, v73
	v_cvt_pk_bf16_f32 v67, v74, v75
	v_cvt_pk_bf16_f32 v68, v68, v69
	v_cvt_pk_bf16_f32 v69, v70, v71
	v_cvt_pk_bf16_f32 v70, v82, v83
	v_cvt_pk_bf16_f32 v71, v84, v85
	global_store_dwordx4 v[80:81], v[64:67], off
	global_store_dwordx4 v[80:81], v[68:71], off offset:256
	s_nop 0
	v_mov_b32_e32 v64, v240
	v_add_u32_e32 v65, 0x80, v146
	v_fmamk_f32 v64, v64, 0x3b000000, v157
	v_mul_f32_e32 v66, 0x4b800000, v64
	v_cmp_gt_f32_e32 vcc, s67, v64
	s_nop 1
	v_cndmask_b32_e32 v64, v64, v66, vcc
	v_rsq_f32_e32 v66, v64
	v_mad_i64_i32 v[64:65], s[48:49], v65, s74, v[148:149]
	v_lshl_add_u64 v[64:65], v[64:65], 0, s[4:5]
	v_mul_f32_e32 v67, 0x45800000, v66
	v_cndmask_b32_e32 v66, v66, v67, vcc
	v_pk_mul_f32 v[62:63], v[62:63], v[66:67] op_sel_hi:[1,0]
	v_pk_mul_f32 v[60:61], v[60:61], v[66:67] op_sel_hi:[1,0]
	v_pk_mul_f32 v[58:59], v[58:59], v[66:67] op_sel_hi:[1,0]
	v_pk_mul_f32 v[56:57], v[56:57], v[66:67] op_sel_hi:[1,0]
	v_lshl_add_u64 v[64:65], v[64:65], 0, v[136:137]
	v_pk_mul_f32 v[54:55], v[54:55], v[66:67] op_sel_hi:[1,0]
	v_pk_mul_f32 v[52:53], v[52:53], v[66:67] op_sel_hi:[1,0]
	v_pk_mul_f32 v[68:69], v[50:51], v[66:67] op_sel_hi:[1,0]
	v_pk_mul_f32 v[66:67], v[48:49], v[66:67] op_sel_hi:[1,0]
	v_cvt_pk_bf16_f32 v48, v60, v61
	v_cvt_pk_bf16_f32 v49, v62, v63
	v_cvt_pk_bf16_f32 v50, v56, v57
	v_cvt_pk_bf16_f32 v51, v58, v59
	v_cvt_pk_bf16_f32 v52, v52, v53
	v_cvt_pk_bf16_f32 v53, v54, v55
	v_cvt_pk_bf16_f32 v54, v66, v67
	v_cvt_pk_bf16_f32 v55, v68, v69
	global_store_dwordx4 v[64:65], v[48:51], off
	global_store_dwordx4 v[64:65], v[52:55], off offset:256
	s_nop 0
	v_mov_b32_e32 v48, v241
	v_add_u32_e32 v49, 0x90, v146
	v_fmamk_f32 v48, v48, 0x3b000000, v157
	v_mul_f32_e32 v50, 0x4b800000, v48
	v_cmp_gt_f32_e32 vcc, s67, v48
	s_nop 1
	v_cndmask_b32_e32 v48, v48, v50, vcc
	v_rsq_f32_e32 v50, v48
	v_mad_i64_i32 v[48:49], s[48:49], v49, s74, v[148:149]
	v_lshl_add_u64 v[48:49], v[48:49], 0, s[4:5]
	v_mul_f32_e32 v51, 0x45800000, v50
	v_cndmask_b32_e32 v50, v50, v51, vcc
	v_pk_mul_f32 v[46:47], v[46:47], v[50:51] op_sel_hi:[1,0]
	v_pk_mul_f32 v[44:45], v[44:45], v[50:51] op_sel_hi:[1,0]
	v_pk_mul_f32 v[42:43], v[42:43], v[50:51] op_sel_hi:[1,0]
	v_pk_mul_f32 v[40:41], v[40:41], v[50:51] op_sel_hi:[1,0]
	v_lshl_add_u64 v[48:49], v[48:49], 0, v[136:137]
	v_pk_mul_f32 v[38:39], v[38:39], v[50:51] op_sel_hi:[1,0]
	v_pk_mul_f32 v[36:37], v[36:37], v[50:51] op_sel_hi:[1,0]
	v_pk_mul_f32 v[52:53], v[34:35], v[50:51] op_sel_hi:[1,0]
	v_pk_mul_f32 v[50:51], v[32:33], v[50:51] op_sel_hi:[1,0]
	v_cvt_pk_bf16_f32 v32, v44, v45
	v_cvt_pk_bf16_f32 v33, v46, v47
	v_cvt_pk_bf16_f32 v34, v40, v41
	v_cvt_pk_bf16_f32 v35, v42, v43
	v_cvt_pk_bf16_f32 v36, v36, v37
	v_cvt_pk_bf16_f32 v37, v38, v39
	v_cvt_pk_bf16_f32 v38, v50, v51
	v_cvt_pk_bf16_f32 v39, v52, v53
	global_store_dwordx4 v[48:49], v[32:35], off
	global_store_dwordx4 v[48:49], v[36:39], off offset:256
	s_nop 0
	v_mov_b32_e32 v32, v242
	v_add_u32_e32 v33, 0xa0, v146
	v_fmamk_f32 v32, v32, 0x3b000000, v157
	v_mul_f32_e32 v34, 0x4b800000, v32
	v_cmp_gt_f32_e32 vcc, s67, v32
	s_nop 1
	v_cndmask_b32_e32 v32, v32, v34, vcc
	v_rsq_f32_e32 v34, v32
	v_mad_i64_i32 v[32:33], s[48:49], v33, s74, v[148:149]
	v_lshl_add_u64 v[32:33], v[32:33], 0, s[4:5]
	v_mul_f32_e32 v35, 0x45800000, v34
	v_cndmask_b32_e32 v34, v34, v35, vcc
	v_pk_mul_f32 v[30:31], v[30:31], v[34:35] op_sel_hi:[1,0]
	v_pk_mul_f32 v[28:29], v[28:29], v[34:35] op_sel_hi:[1,0]
	v_pk_mul_f32 v[26:27], v[26:27], v[34:35] op_sel_hi:[1,0]
	v_pk_mul_f32 v[24:25], v[24:25], v[34:35] op_sel_hi:[1,0]
	v_lshl_add_u64 v[32:33], v[32:33], 0, v[136:137]
	v_pk_mul_f32 v[22:23], v[22:23], v[34:35] op_sel_hi:[1,0]
	v_pk_mul_f32 v[20:21], v[20:21], v[34:35] op_sel_hi:[1,0]
	v_pk_mul_f32 v[36:37], v[18:19], v[34:35] op_sel_hi:[1,0]
	v_pk_mul_f32 v[34:35], v[16:17], v[34:35] op_sel_hi:[1,0]
	v_cvt_pk_bf16_f32 v16, v28, v29
	v_cvt_pk_bf16_f32 v17, v30, v31
	v_cvt_pk_bf16_f32 v18, v24, v25
	v_cvt_pk_bf16_f32 v19, v26, v27
	v_cvt_pk_bf16_f32 v20, v20, v21
	v_cvt_pk_bf16_f32 v21, v22, v23
	v_cvt_pk_bf16_f32 v22, v34, v35
	v_cvt_pk_bf16_f32 v23, v36, v37
	global_store_dwordx4 v[32:33], v[16:19], off
	global_store_dwordx4 v[32:33], v[20:23], off offset:256
	s_nop 0
	v_mov_b32_e32 v16, v243
	s_and_b64 vcc, exec, s[0:1]
	v_add_u32_e32 v17, 0xb0, v146
	v_fmamk_f32 v16, v16, 0x3b000000, v157
	v_mul_f32_e32 v18, 0x4b800000, v16
	v_cmp_gt_f32_e64 s[0:1], s67, v16
	s_nop 1
	v_cndmask_b32_e64 v16, v16, v18, s[0:1]
	v_rsq_f32_e32 v18, v16
	v_mad_i64_i32 v[16:17], s[48:49], v17, s74, v[148:149]
	v_lshl_add_u64 v[16:17], v[16:17], 0, s[4:5]
	v_mul_f32_e32 v19, 0x45800000, v18
	v_cndmask_b32_e64 v18, v18, v19, s[0:1]
	v_pk_mul_f32 v[14:15], v[14:15], v[18:19] op_sel_hi:[1,0]
	v_pk_mul_f32 v[12:13], v[12:13], v[18:19] op_sel_hi:[1,0]
	v_pk_mul_f32 v[10:11], v[10:11], v[18:19] op_sel_hi:[1,0]
	v_pk_mul_f32 v[8:9], v[8:9], v[18:19] op_sel_hi:[1,0]
	v_lshl_add_u64 v[16:17], v[16:17], 0, v[136:137]
	v_pk_mul_f32 v[6:7], v[6:7], v[18:19] op_sel_hi:[1,0]
	v_pk_mul_f32 v[4:5], v[4:5], v[18:19] op_sel_hi:[1,0]
	v_pk_mul_f32 v[20:21], v[2:3], v[18:19] op_sel_hi:[1,0]
	v_pk_mul_f32 v[18:19], v[0:1], v[18:19] op_sel_hi:[1,0]
	v_cvt_pk_bf16_f32 v0, v12, v13
	v_cvt_pk_bf16_f32 v1, v14, v15
	v_cvt_pk_bf16_f32 v2, v8, v9
	v_cvt_pk_bf16_f32 v3, v10, v11
	s_mov_b64 s[0:1], -1
	v_cvt_pk_bf16_f32 v4, v4, v5
	v_cvt_pk_bf16_f32 v5, v6, v7
	v_cvt_pk_bf16_f32 v6, v18, v19
	v_cvt_pk_bf16_f32 v7, v20, v21
	global_store_dwordx4 v[16:17], v[0:3], off
	global_store_dwordx4 v[16:17], v[4:7], off offset:256
	s_cbranch_vccnz .LBB0_710
	s_andn2_b64 vcc, exec, s[16:17]
	s_cbranch_vccnz .LBB0_709
	s_barrier
	s_branch .LBB0_709
